# GEMM tile loops (phase A / C): one static s_setprio 1 for waves 4-7 before the K loop, reset after it
# speedup vs baseline: 1.0020x; 1.0020x over previous
.LBB0_94:
	s_ashr_i32 s0, s2, 31
	s_lshr_b32 s0, s0, 29
	s_add_i32 s0, s2, s0
	v_mov_b32_e32 v78, v133
	s_and_b32 s1, s0, 0x1fffff8
	s_lshl_b32 s0, s0, 5
	s_and_b32 s22, s0, 0xffffff00
	v_ashrrev_i32_e32 v6, 6, v78
	v_bfe_u32 v7, v78, 3, 3
	v_lshl_or_b32 v8, v6, 5, v7
	v_add_u32_e32 v0, s22, v8
	s_waitcnt lgkmcnt(0)
	v_ashrrev_i32_e32 v1, 31, v0
	v_lshlrev_b64 v[2:3], 11, v[0:1]
	v_bfe_u32 v1, v78, 4, 2
	v_readlane_b32 s20, v214, 4
	v_xor_b32_e32 v1, v1, v78
	v_readlane_b32 s21, v214, 5
	v_lshlrev_b32_e32 v1, 4, v1
	v_and_b32_e32 v64, 0x70, v1
	v_lshl_add_u64 v[2:3], s[20:21], 0, v[2:3]
	v_or_b32_e32 v1, 8, v8
	v_lshl_add_u64 v[66:67], v[2:3], 0, v[64:65]
	v_add_u32_e32 v2, s22, v1
	v_lshrrev_b32_e32 v1, 1, v1
	v_xor_b32_e32 v1, v1, v78
	v_ashrrev_i32_e32 v3, 31, v2
	v_lshlrev_b32_e32 v1, 4, v1
	v_or_b32_e32 v0, 16, v0
	v_lshlrev_b64 v[2:3], 11, v[2:3]
	v_and_b32_e32 v4, 0x70, v1
	v_ashrrev_i32_e32 v1, 31, v0
	v_lshl_add_u64 v[2:3], s[20:21], 0, v[2:3]
	v_mov_b32_e32 v5, v65
	v_lshlrev_b64 v[0:1], 11, v[0:1]
	v_lshl_add_u64 v[68:69], v[2:3], 0, v[4:5]
	v_lshl_add_u64 v[0:1], s[20:21], 0, v[0:1]
	v_or_b32_e32 v2, 24, v8
	v_lshl_add_u64 v[70:71], v[0:1], 0, v[64:65]
	v_add_u32_e32 v0, s22, v2
	v_lshrrev_b32_e32 v2, 1, v2
	v_ashrrev_i32_e32 v1, 31, v0
	v_xor_b32_e32 v2, v2, v78
	v_lshlrev_b64 v[0:1], 11, v[0:1]
	v_lshlrev_b32_e32 v2, 4, v2
	s_sub_i32 s1, s2, s1
	v_lshl_add_u64 v[0:1], s[20:21], 0, v[0:1]
	v_and_b32_e32 v2, 0x70, v2
	v_mov_b32_e32 v3, v65
	s_lshl_b32 s0, s1, 7
	v_lshl_add_u64 v[72:73], v[0:1], 0, v[2:3]
	v_lshl_or_b32 v2, v6, 4, v7
	v_add_u32_e32 v0, s0, v2
	v_lshlrev_b32_e32 v3, 12, v6
	v_ashrrev_i32_e32 v1, 31, v0
	v_add_u32_e32 v126, 0, v3
	v_lshlrev_b64 v[0:1], 11, v[0:1]
	s_waitcnt vmcnt(0)
	v_readfirstlane_b32 s38, v126
	v_add_u32_e32 v127, 0x400, v126
	v_lshl_add_u64 v[0:1], s[40:41], 0, v[0:1]
	v_or_b32_e32 v2, 8, v2
	s_waitcnt lgkmcnt(0)
	s_barrier
	s_mov_b32 m0, s38
	v_readfirstlane_b32 s39, v127
	v_add_u32_e32 v128, 0x800, v126
	v_lshlrev_b32_e32 v5, 11, v6
	v_and_b32_e32 v80, 1, v6
	v_lshl_add_u64 v[74:75], v[0:1], 0, v[64:65]
	v_add_u32_e32 v0, s0, v2
	v_lshrrev_b32_e32 v2, 1, v2
	global_load_lds_dwordx4 v[66:67], off
	s_mov_b32 m0, s39
	v_readfirstlane_b32 s48, v128
	v_add_u32_e32 v129, 0xc00, v126
	v_add_u32_e32 v6, 0, v5
	v_ashrrev_i32_e32 v1, 31, v0
	v_xor_b32_e32 v2, v2, v78
	global_load_lds_dwordx4 v[68:69], off
	s_mov_b32 m0, s48
	v_readfirstlane_b32 s49, v129
	v_add_u32_e32 v131, 0x8000, v6
	v_lshlrev_b64 v[0:1], 11, v[0:1]
	v_lshlrev_b32_e32 v2, 4, v2
	global_load_lds_dwordx4 v[70:71], off
	s_mov_b32 m0, s49
	v_readfirstlane_b32 s53, v131
	v_add_u32_e32 v130, 0x8400, v6
	v_lshl_add_u64 v[0:1], s[40:41], 0, v[0:1]
	v_and_b32_e32 v64, 0x70, v2
	global_load_lds_dwordx4 v[72:73], off
	s_mov_b32 m0, s53
	v_readfirstlane_b32 s54, v130
	v_add_u32_e32 v120, 0xc000, v126
	v_lshl_add_u64 v[76:77], v[0:1], 0, v[64:65]
	global_load_lds_dwordx4 v[74:75], off
	s_mov_b32 m0, s54
	s_mov_b64 s[20:21], 0x80
	v_readfirstlane_b32 s29, v120
	v_add_u32_e32 v121, 0xc400, v126
	global_load_lds_dwordx4 v[76:77], off
	v_lshl_add_u64 v[0:1], v[66:67], 0, s[20:21]
	s_mov_b32 m0, s29
	v_readfirstlane_b32 s33, v121
	v_add_u32_e32 v122, 0xc800, v126
	global_load_lds_dwordx4 v[0:1], off
	v_lshl_add_u64 v[0:1], v[68:69], 0, s[20:21]
	s_mov_b32 m0, s33
	v_readfirstlane_b32 s34, v122
	v_add_u32_e32 v123, 0xcc00, v126
	global_load_lds_dwordx4 v[0:1], off
	v_lshl_add_u64 v[0:1], v[70:71], 0, s[20:21]
	s_mov_b32 m0, s34
	v_readfirstlane_b32 s35, v123
	v_add_u32_e32 v124, s85, v5
	global_load_lds_dwordx4 v[0:1], off
	v_lshl_add_u64 v[0:1], v[72:73], 0, s[20:21]
	s_mov_b32 m0, s35
	v_readfirstlane_b32 s36, v124
	v_add_u32_e32 v125, 0x14400, v6
	global_load_lds_dwordx4 v[0:1], off
	v_lshl_add_u64 v[0:1], v[74:75], 0, s[20:21]
	s_mov_b32 m0, s36
	v_readfirstlane_b32 s37, v125
	global_load_lds_dwordx4 v[0:1], off
	v_lshl_add_u64 v[0:1], v[76:77], 0, s[20:21]
	s_mov_b32 m0, s37
	v_lshrrev_b32_e32 v2, 1, v78
	v_bfe_u32 v64, v78, 5, 1
	global_load_lds_dwordx4 v[0:1], off
	v_add_u32_e32 v114, s3, v3
	v_bitop3_b32 v0, v2, v64, 7 bitop3:0x6c
	s_waitcnt vmcnt(6)
	s_mov_b64 s[30:31], 0x100
	v_readfirstlane_b32 s1, v114
	v_add_u32_e32 v115, 0x400, v114
	v_lshlrev_b32_e32 v132, 4, v0
	s_waitcnt lgkmcnt(0)
	s_barrier
	v_lshl_add_u64 v[0:1], v[66:67], 0, s[30:31]
	s_mov_b32 m0, s1
	v_readfirstlane_b32 s20, v115
	v_add_u32_e32 v116, 0x800, v114
	global_load_lds_dwordx4 v[0:1], off
	v_lshl_add_u64 v[0:1], v[68:69], 0, s[30:31]
	s_mov_b32 m0, s20
	v_readfirstlane_b32 s21, v116
	v_add_u32_e32 v117, 0xc00, v114
	v_readlane_b32 s24, v212, 31
	v_and_b32_e32 v79, 31, v78
	global_load_lds_dwordx4 v[0:1], off
	v_lshl_add_u64 v[0:1], v[70:71], 0, s[30:31]
	s_mov_b32 m0, s21
	v_readfirstlane_b32 s23, v117
	v_add_u32_e32 v118, s24, v5
	v_add_u32_e32 v2, s3, v5
	v_lshlrev_b32_e32 v4, 7, v79
	global_load_lds_dwordx4 v[0:1], off
	v_lshl_add_u64 v[0:1], v[72:73], 0, s[30:31]
	s_mov_b32 m0, s23
	v_readfirstlane_b32 s24, v118
	v_add_u32_e32 v119, 0x8400, v2
	v_lshl_or_b32 v102, v80, 13, v4
	global_load_lds_dwordx4 v[0:1], off
	v_lshl_add_u64 v[0:1], v[74:75], 0, s[30:31]
	s_mov_b32 m0, s24
	v_readfirstlane_b32 s28, v119
	global_load_lds_dwordx4 v[0:1], off
	v_lshl_add_u64 v[0:1], v[76:77], 0, s[30:31]
	s_mov_b32 m0, s28
	v_add_u32_e32 v100, 0, v102
	global_load_lds_dwordx4 v[0:1], off
	v_add_u32_e32 v83, v100, v132
	v_ashrrev_i32_e32 v81, 7, v78
	ds_read_b128 a[0:3], v83 offset:32768
	ds_read_b128 a[4:7], v83 offset:36864
	v_lshl_or_b32 v134, v81, 13, v4
	v_add_u32_e32 v101, 0, v134
	v_add_u32_e32 v82, v101, v132
	ds_read_b128 a[8:11], v82
	ds_read_b128 a[12:15], v82 offset:4096
	v_lshrrev_b32_e32 v182, 6, v133
	s_nop 0
	v_readfirstlane_b32 s32, v182
	s_cmp_ge_u32 s32, 4
	s_cbranch_scc0 .Lmy_prio0
	s_setprio 1
.Lmy_prio0:
	s_waitcnt lgkmcnt(1)
	v_mfma_f32_32x32x16_bf16 v[48:63], a[0:3], a[8:11], 0
	v_bfe_u32 v103, v78, 1, 3
	s_mov_b64 s[30:31], 0x180
	s_nop 0
	v_or_b32_e32 v143, 0x8000, v102
	v_or_b32_e32 v144, 0x9000, v102
	v_add_u32_e32 v145, s3, v134
	v_lshl_or_b32 v81, v81, 6, v79
	s_waitcnt vmcnt(12)
	v_mfma_f32_32x32x16_bf16 v[32:47], a[4:7], a[8:11], 0
	v_mul_lo_u32 v81, v81, s26
	s_mov_b64 s[80:81], 0x200
	s_waitcnt lgkmcnt(0)
	v_mfma_f32_32x32x16_bf16 v[16:31], a[0:3], a[12:15], 0
	v_bitop3_b32 v0, v64, v103, 2 bitop3:0x36
	v_lshlrev_b32_e32 v138, 4, v0
	v_add_u32_e32 v84, v101, v138
	ds_read_b128 a[28:31], v84 offset:4096
	s_nop 0
	s_nop 0
	ds_read_b128 a[24:27], v84
	s_nop 0
	v_add_u32_e32 v85, v100, v138
	ds_read_b128 a[20:23], v85 offset:36864
	s_nop 0
	s_nop 0
	ds_read_b128 a[16:19], v85 offset:32768
	s_nop 0
	s_nop 0
	s_nop 0
	s_nop 0
	s_nop 0
	s_nop 0
	v_mfma_f32_32x32x16_bf16 v[0:15], a[4:7], a[12:15], 0
	s_nop 0
	s_waitcnt lgkmcnt(0)
	v_mfma_f32_32x32x16_bf16 v[48:63], a[16:19], a[24:27], v[48:63]
	v_mfma_f32_32x32x16_bf16 v[32:47], a[20:23], a[24:27], v[32:47]
	v_mfma_f32_32x32x16_bf16 v[16:31], a[16:19], a[28:31], v[16:31]
	v_bitop3_b32 v86, v64, v103, 4 bitop3:0x36
	v_lshlrev_b32_e32 v139, 4, v86
	v_add_u32_e32 v86, v101, v139
	ds_read_b128 a[12:15], v86 offset:4096
	s_nop 0
	s_nop 0
	ds_read_b128 a[8:11], v86
	s_nop 0
	v_add_u32_e32 v87, v100, v139
	ds_read_b128 a[4:7], v87 offset:36864
	s_nop 0
	s_nop 0
	ds_read_b128 a[0:3], v87 offset:32768
	s_nop 0
	s_nop 0
	s_nop 0
	v_mfma_f32_32x32x16_bf16 v[0:15], a[20:23], a[28:31], v[0:15]
	s_nop 0
	s_nop 0
	s_nop 0
	s_nop 0
	s_waitcnt lgkmcnt(0)
	v_mfma_f32_32x32x16_bf16 v[48:63], a[0:3], a[8:11], v[48:63]
	v_mfma_f32_32x32x16_bf16 v[32:47], a[4:7], a[8:11], v[32:47]
	v_mfma_f32_32x32x16_bf16 v[16:31], a[0:3], a[12:15], v[16:31]
	v_bitop3_b32 v88, v64, v103, 6 bitop3:0x36
	v_lshlrev_b32_e32 v142, 4, v88
	v_add_u32_e32 v88, v101, v142
	ds_read_b128 a[28:31], v88 offset:4096
	s_nop 0
	s_nop 0
	ds_read_b128 a[24:27], v88
	s_nop 0
	v_add_u32_e32 v89, v100, v142
	ds_read_b128 a[20:23], v89 offset:36864
	s_nop 0
	s_nop 0
	ds_read_b128 a[16:19], v89 offset:32768
	s_nop 0
	s_nop 0
	s_nop 0
	v_lshlrev_b32_e32 v64, 4, v64
	v_lshl_or_b32 v64, v80, 8, v64
	v_add3_u32 v64, 0, v81, v64
	v_mfma_f32_32x32x16_bf16 v[0:15], a[4:7], a[12:15], v[0:15]
	s_nop 0
	s_nop 0
	s_nop 0
	s_nop 0
	s_waitcnt lgkmcnt(0)
	v_mfma_f32_32x32x16_bf16 v[48:63], a[16:19], a[24:27], v[48:63]
	v_mfma_f32_32x32x16_bf16 v[32:47], a[20:23], a[24:27], v[32:47]
	s_waitcnt vmcnt(6)
	s_waitcnt lgkmcnt(0)
	s_barrier
	ds_read_b128 a[12:15], v82 offset:53248
	ds_read_b128 a[8:11], v82 offset:49152
	v_mfma_f32_32x32x16_bf16 v[16:31], a[16:19], a[28:31], v[16:31]
	v_lshl_add_u64 v[158:159], v[66:67], 0, s[30:31]
	s_nop 0
	v_lshl_add_u64 v[160:161], v[68:69], 0, s[30:31]
	s_nop 0
	s_nop 0
	s_nop 0
	v_lshl_add_u64 v[162:163], v[70:71], 0, s[30:31]
	s_nop 0
	v_mfma_f32_32x32x16_bf16 v[0:15], a[20:23], a[28:31], v[0:15]
	s_and_b32 m0, s32, 7
	s_lshl_b32 m0, m0, 12
	s_add_i32 m0, m0, 0x0
	s_nop 0
	global_load_lds_dwordx4 v[158:159], off
	s_nop 0
	v_lshl_add_u64 v[164:165], v[72:73], 0, s[30:31]
	s_nop 0
	s_nop 0
	s_nop 0
	v_lshl_add_u64 v[166:167], v[74:75], 0, s[30:31]
	s_nop 0
	s_nop 0
	s_nop 0
	v_lshl_add_u64 v[168:169], v[76:77], 0, s[30:31]
	s_nop 0
	s_add_i32 s30, 0, 0xc000
	v_add_u32_e32 v90, s30, v132
	v_add_u32_e32 v92, v90, v143
	v_add_u32_e32 v90, v90, v144
	ds_read_b128 a[4:7], v90
	ds_read_b128 a[0:3], v92
	s_nop 0
	s_nop 0
	s_nop 0
	s_nop 0
	s_nop 0
	s_nop 0
	s_nop 0
	s_nop 0
	v_add_u32_e32 v91, s30, v138
	v_add_u32_e32 v93, v91, v143
	ds_read_b128 a[16:19], v93
	v_add_u32_e32 v91, v91, v144
	ds_read_b128 a[20:23], v91
	ds_read_b128 a[24:27], v84 offset:49152
	ds_read_b128 a[28:31], v84 offset:53248
	s_waitcnt lgkmcnt(4)
	v_mfma_f32_32x32x16_bf16 v[48:63], a[0:3], a[8:11], v[48:63]
	s_nop 0
	s_nop 0
	s_nop 0
	s_nop 0
	v_mfma_f32_32x32x16_bf16 v[32:47], a[4:7], a[8:11], v[32:47]
	s_and_b32 m0, s32, 7
	s_lshl_b32 m0, m0, 12
	s_add_i32 m0, m0, 0x400
	s_nop 0
	global_load_lds_dwordx4 v[160:161], off
	v_mfma_f32_32x32x16_bf16 v[16:31], a[0:3], a[12:15], v[16:31]
	v_mfma_f32_32x32x16_bf16 v[0:15], a[4:7], a[12:15], v[0:15]
	s_and_b32 m0, s32, 7
	s_lshl_b32 m0, m0, 12
	s_add_i32 m0, m0, 0x800
	s_nop 0
	global_load_lds_dwordx4 v[162:163], off
	s_nop 0
	s_nop 0
	s_nop 0
	s_nop 0
	v_add_u32_e32 v94, s30, v139
	v_add_u32_e32 v95, v94, v143
	ds_read_b128 a[0:3], v95
	v_add_u32_e32 v94, v94, v144
	ds_read_b128 a[4:7], v94
	ds_read_b128 a[8:11], v86 offset:49152
	ds_read_b128 a[12:15], v86 offset:53248
	s_waitcnt lgkmcnt(5)
	v_mfma_f32_32x32x16_bf16 v[48:63], a[16:19], a[24:27], v[48:63]
	v_mfma_f32_32x32x16_bf16 v[32:47], a[20:23], a[24:27], v[32:47]
	s_and_b32 m0, s32, 7
	s_lshl_b32 m0, m0, 12
	s_add_i32 m0, m0, 0xc00
	s_nop 0
	global_load_lds_dwordx4 v[164:165], off
	s_waitcnt lgkmcnt(4)
	v_mfma_f32_32x32x16_bf16 v[16:31], a[16:19], a[28:31], v[16:31]
	s_nop 0
	s_nop 0
	s_nop 0
	v_mfma_f32_32x32x16_bf16 v[0:15], a[20:23], a[28:31], v[0:15]
	s_and_b32 m0, s32, 7
	s_lshl_b32 m0, m0, 11
	s_add_i32 m0, m0, 0x8000
	s_nop 0
	global_load_lds_dwordx4 v[166:167], off
	s_nop 0
	s_nop 0
	s_nop 0
	s_nop 0
	v_add_u32_e32 v96, s30, v142
	v_add_u32_e32 v97, v96, v143
	ds_read_b128 a[16:19], v97
	v_add_u32_e32 v96, v96, v144
	ds_read_b128 a[20:23], v96
	ds_read_b128 a[24:27], v88 offset:49152
	ds_read_b128 a[28:31], v88 offset:53248
	s_waitcnt lgkmcnt(5)
	v_mfma_f32_32x32x16_bf16 v[48:63], a[0:3], a[8:11], v[48:63]
	v_mfma_f32_32x32x16_bf16 v[32:47], a[4:7], a[8:11], v[32:47]
	s_and_b32 m0, s32, 7
	s_lshl_b32 m0, m0, 11
	s_add_i32 m0, m0, 0x8400
	s_nop 0
	global_load_lds_dwordx4 v[168:169], off
	s_waitcnt lgkmcnt(4)
	v_mfma_f32_32x32x16_bf16 v[16:31], a[0:3], a[12:15], v[16:31]
	s_nop 0
	s_nop 0
	s_nop 0
	s_mov_b64 s[30:31], 0x200
	v_mfma_f32_32x32x16_bf16 v[0:15], a[4:7], a[12:15], v[0:15]
	s_nop 0
	s_nop 0
	s_nop 0
	s_nop 0
	s_waitcnt lgkmcnt(1)
	v_mfma_f32_32x32x16_bf16 v[48:63], a[16:19], a[24:27], v[48:63]
	v_mfma_f32_32x32x16_bf16 v[32:47], a[20:23], a[24:27], v[32:47]
	s_waitcnt vmcnt(6)
	s_waitcnt lgkmcnt(0)
	s_barrier
	v_add_u32_e32 v100, v145, v132
	ds_read_b128 a[8:11], v100
	v_add_u32_e32 v101, s3, v132
	v_add_u32_e32 v99, v101, v144
	ds_read_b128 a[4:7], v99
	s_nop 0
	v_add_u32_e32 v98, v101, v143
	v_or_b32_e32 v132, 0x1000, v134
	v_add_u32_e32 v101, v101, v132
	ds_read_b128 a[12:15], v101
	ds_read_b128 a[0:3], v98
	v_mfma_f32_32x32x16_bf16 v[16:31], a[16:19], a[28:31], v[16:31]
	v_lshl_add_u64 v[170:171], v[66:67], 0, s[30:31]
	s_nop 0
	v_lshl_add_u64 v[172:173], v[68:69], 0, s[30:31]
	s_nop 0
	s_nop 0
	s_nop 0
	v_lshl_add_u64 v[174:175], v[70:71], 0, s[30:31]
	s_nop 0
	v_mfma_f32_32x32x16_bf16 v[0:15], a[20:23], a[28:31], v[0:15]
	s_and_b32 m0, s32, 7
	s_lshl_b32 m0, m0, 12
	s_add_i32 m0, m0, 0xc000
	s_nop 0
	global_load_lds_dwordx4 v[170:171], off
	s_nop 0
	v_lshl_add_u64 v[176:177], v[72:73], 0, s[30:31]
	s_nop 0
	s_nop 0
	s_nop 0
	v_lshl_add_u64 v[178:179], v[74:75], 0, s[30:31]
	s_nop 0
	s_nop 0
	s_nop 0
	v_lshl_add_u64 v[180:181], v[76:77], 0, s[30:31]
	s_nop 0
	s_mov_b64 s[30:31], 0x280
	s_nop 0
	s_nop 0
	s_nop 0
	s_nop 0
	s_nop 0
	s_nop 0
	s_nop 0
	s_nop 0
	v_add_u32_e32 v105, s3, v138
	v_add_u32_e32 v102, v105, v143
	ds_read_b128 a[16:19], v102
	v_add_u32_e32 v103, v105, v144
	ds_read_b128 a[20:23], v103
	v_add_u32_e32 v104, v145, v138
	ds_read_b128 a[24:27], v104
	v_add_u32_e32 v105, v105, v132
	ds_read_b128 a[28:31], v105
	s_waitcnt lgkmcnt(4)
	v_mfma_f32_32x32x16_bf16 v[48:63], a[0:3], a[8:11], v[48:63]
	s_nop 0
	v_mfma_f32_32x32x16_bf16 v[32:47], a[4:7], a[8:11], v[32:47]
	s_and_b32 m0, s32, 7
	s_lshl_b32 m0, m0, 12
	s_add_i32 m0, m0, 0xc400
	s_nop 0
	global_load_lds_dwordx4 v[172:173], off
	s_nop 0
	s_nop 0
	s_nop 0
	s_nop 0
	s_nop 0
	v_mfma_f32_32x32x16_bf16 v[16:31], a[0:3], a[12:15], v[16:31]
	s_nop 0
	v_mfma_f32_32x32x16_bf16 v[0:15], a[4:7], a[12:15], v[0:15]
	s_and_b32 m0, s32, 7
	s_lshl_b32 m0, m0, 12
	s_add_i32 m0, m0, 0xc800
	s_nop 0
	global_load_lds_dwordx4 v[174:175], off
	s_nop 0
	s_nop 0
	s_nop 0
	v_add_u32_e32 v109, s3, v139
	v_add_u32_e32 v106, v109, v143
	ds_read_b128 a[0:3], v106
	v_add_u32_e32 v107, v109, v144
	ds_read_b128 a[4:7], v107
	v_add_u32_e32 v108, v145, v139
	ds_read_b128 a[8:11], v108
	v_add_u32_e32 v109, v109, v132
	ds_read_b128 a[12:15], v109
	s_waitcnt lgkmcnt(5)
	v_mfma_f32_32x32x16_bf16 v[48:63], a[16:19], a[24:27], v[48:63]
	v_mfma_f32_32x32x16_bf16 v[32:47], a[20:23], a[24:27], v[32:47]
	s_and_b32 m0, s32, 7
	s_lshl_b32 m0, m0, 12
	s_add_i32 m0, m0, 0xcc00
	s_nop 0
	global_load_lds_dwordx4 v[176:177], off
	s_waitcnt lgkmcnt(4)
	v_mfma_f32_32x32x16_bf16 v[16:31], a[16:19], a[28:31], v[16:31]
	s_nop 0
	s_nop 0
	s_nop 0
	s_nop 0
	s_nop 0
	s_nop 0
	v_mfma_f32_32x32x16_bf16 v[0:15], a[20:23], a[28:31], v[0:15]
	s_and_b32 m0, s32, 7
	s_lshl_b32 m0, m0, 11
	s_add_i32 m0, m0, 0x14000
	s_nop 0
	global_load_lds_dwordx4 v[178:179], off
	s_nop 0
	s_nop 0
	s_nop 0
	v_add_u32_e32 v113, s3, v142
	v_add_u32_e32 v110, v113, v143
	ds_read_b128 a[16:19], v110
	v_add_u32_e32 v111, v113, v144
	ds_read_b128 a[20:23], v111
	v_add_u32_e32 v112, v145, v142
	ds_read_b128 a[24:27], v112
	v_add_u32_e32 v113, v113, v132
	ds_read_b128 a[28:31], v113
	s_waitcnt lgkmcnt(5)
	v_mfma_f32_32x32x16_bf16 v[48:63], a[0:3], a[8:11], v[48:63]
	v_mfma_f32_32x32x16_bf16 v[32:47], a[4:7], a[8:11], v[32:47]
	s_and_b32 m0, s32, 7
	s_lshl_b32 m0, m0, 11
	s_add_i32 m0, m0, 0x14400
	s_nop 0
	global_load_lds_dwordx4 v[180:181], off
	s_waitcnt lgkmcnt(4)
	v_mfma_f32_32x32x16_bf16 v[16:31], a[0:3], a[12:15], v[16:31]
	s_nop 0
	s_nop 0
	s_nop 0
	s_nop 0
	s_nop 0
	s_nop 0
	v_mfma_f32_32x32x16_bf16 v[0:15], a[4:7], a[12:15], v[0:15]
	s_nop 0
	s_nop 0
	s_nop 0
	s_waitcnt lgkmcnt(1)
	v_mfma_f32_32x32x16_bf16 v[48:63], a[16:19], a[24:27], v[48:63]
	v_mfma_f32_32x32x16_bf16 v[32:47], a[20:23], a[24:27], v[32:47]
	s_waitcnt vmcnt(6)
	s_waitcnt lgkmcnt(0)
	s_barrier
	ds_read_b128 a[12:15], v82 offset:4096
	ds_read_b128 a[8:11], v82
	ds_read_b128 a[4:7], v83 offset:36864
	ds_read_b128 a[0:3], v83 offset:32768
	v_mfma_f32_32x32x16_bf16 v[16:31], a[16:19], a[28:31], v[16:31]
	v_lshl_add_u64 v[158:159], v[66:67], 0, s[30:31]
	s_nop 0
	v_lshl_add_u64 v[160:161], v[68:69], 0, s[30:31]
	s_nop 0
	s_nop 0
	s_nop 0
	v_lshl_add_u64 v[162:163], v[70:71], 0, s[30:31]
	s_nop 0
	v_mfma_f32_32x32x16_bf16 v[0:15], a[20:23], a[28:31], v[0:15]
	s_and_b32 m0, s32, 7
	s_lshl_b32 m0, m0, 12
	s_add_i32 m0, m0, 0x18000
	s_nop 0
	global_load_lds_dwordx4 v[158:159], off
	s_nop 0
	v_lshl_add_u64 v[164:165], v[72:73], 0, s[30:31]
	s_nop 0
	s_nop 0
	s_nop 0
	v_lshl_add_u64 v[166:167], v[74:75], 0, s[30:31]
	s_nop 0
	s_nop 0
	s_nop 0
	v_lshl_add_u64 v[168:169], v[76:77], 0, s[30:31]
	s_nop 0
	s_mov_b64 s[30:31], 0x300
	s_nop 0
	s_nop 0
	s_nop 0
	s_nop 0
	s_nop 0
	ds_read_b128 a[16:19], v85 offset:32768
	ds_read_b128 a[20:23], v85 offset:36864
	ds_read_b128 a[24:27], v84
	ds_read_b128 a[28:31], v84 offset:4096
	s_waitcnt lgkmcnt(4)
	v_mfma_f32_32x32x16_bf16 v[48:63], a[0:3], a[8:11], v[48:63]
	s_nop 0
	v_readfirstlane_b32 s38, v114
	v_mfma_f32_32x32x16_bf16 v[32:47], a[4:7], a[8:11], v[32:47]
	s_and_b32 m0, s32, 7
	s_lshl_b32 m0, m0, 12
	s_add_i32 m0, m0, 0x18400
	s_nop 0
	global_load_lds_dwordx4 v[160:161], off
	v_mfma_f32_32x32x16_bf16 v[16:31], a[0:3], a[12:15], v[16:31]
	v_mfma_f32_32x32x16_bf16 v[0:15], a[4:7], a[12:15], v[0:15]
	s_and_b32 m0, s32, 7
	s_lshl_b32 m0, m0, 12
	s_add_i32 m0, m0, 0x18800
	s_nop 0
	global_load_lds_dwordx4 v[162:163], off
	s_nop 0
	s_nop 0
	s_nop 0
	s_nop 0
	ds_read_b128 a[0:3], v87 offset:32768
	ds_read_b128 a[4:7], v87 offset:36864
	ds_read_b128 a[8:11], v86
	ds_read_b128 a[12:15], v86 offset:4096
	s_waitcnt lgkmcnt(5)
	v_mfma_f32_32x32x16_bf16 v[48:63], a[16:19], a[24:27], v[48:63]
	v_mfma_f32_32x32x16_bf16 v[32:47], a[20:23], a[24:27], v[32:47]
	s_and_b32 m0, s32, 7
	s_lshl_b32 m0, m0, 12
	s_add_i32 m0, m0, 0x18c00
	s_nop 0
	global_load_lds_dwordx4 v[164:165], off
	s_waitcnt lgkmcnt(4)
	v_mfma_f32_32x32x16_bf16 v[16:31], a[16:19], a[28:31], v[16:31]
	v_mfma_f32_32x32x16_bf16 v[0:15], a[20:23], a[28:31], v[0:15]
	s_and_b32 m0, s32, 7
	s_lshl_b32 m0, m0, 11
	s_add_i32 m0, m0, 0x20000
	s_nop 0
	global_load_lds_dwordx4 v[166:167], off
	s_nop 0
	s_nop 0
	s_nop 0
	s_nop 0
	ds_read_b128 a[16:19], v89 offset:32768
	ds_read_b128 a[20:23], v89 offset:36864
	ds_read_b128 a[24:27], v88
	ds_read_b128 a[28:31], v88 offset:4096
	s_waitcnt lgkmcnt(5)
	v_mfma_f32_32x32x16_bf16 v[48:63], a[0:3], a[8:11], v[48:63]
	v_mfma_f32_32x32x16_bf16 v[32:47], a[4:7], a[8:11], v[32:47]
	s_and_b32 m0, s32, 7
	s_lshl_b32 m0, m0, 11
	s_add_i32 m0, m0, 0x20400
	s_nop 0
	global_load_lds_dwordx4 v[168:169], off
	s_waitcnt lgkmcnt(4)
	v_mfma_f32_32x32x16_bf16 v[16:31], a[0:3], a[12:15], v[16:31]
	v_mfma_f32_32x32x16_bf16 v[0:15], a[4:7], a[12:15], v[0:15]
	s_nop 0
	s_nop 0
	s_nop 0
	s_nop 0
	s_waitcnt lgkmcnt(1)
	v_mfma_f32_32x32x16_bf16 v[48:63], a[16:19], a[24:27], v[48:63]
	v_mfma_f32_32x32x16_bf16 v[32:47], a[20:23], a[24:27], v[32:47]
	s_waitcnt vmcnt(6)
	s_waitcnt lgkmcnt(0)
	s_barrier
	ds_read_b128 a[12:15], v82 offset:53248
	ds_read_b128 a[8:11], v82 offset:49152
	ds_read_b128 a[4:7], v90
	ds_read_b128 a[0:3], v92
	v_mfma_f32_32x32x16_bf16 v[16:31], a[16:19], a[28:31], v[16:31]
	v_lshl_add_u64 v[170:171], v[66:67], 0, s[30:31]
	s_nop 0
	v_lshl_add_u64 v[172:173], v[68:69], 0, s[30:31]
	s_nop 0
	v_readfirstlane_b32 s39, v115
	s_nop 0
	v_lshl_add_u64 v[174:175], v[70:71], 0, s[30:31]
	s_nop 0
	v_mfma_f32_32x32x16_bf16 v[0:15], a[20:23], a[28:31], v[0:15]
	s_and_b32 m0, s32, 7
	s_lshl_b32 m0, m0, 12
	s_add_i32 m0, m0, 0x0
	s_nop 0
	global_load_lds_dwordx4 v[170:171], off
	s_nop 0
	v_lshl_add_u64 v[176:177], v[72:73], 0, s[30:31]
	s_nop 0
	v_readfirstlane_b32 s48, v116
	s_nop 0
	v_lshl_add_u64 v[178:179], v[74:75], 0, s[30:31]
	s_nop 0
	v_readfirstlane_b32 s49, v117
	s_nop 0
	v_lshl_add_u64 v[180:181], v[76:77], 0, s[30:31]
	s_nop 0
	s_mov_b64 s[30:31], 0x380
	s_nop 0
	s_nop 0
	s_nop 0
	s_nop 0
	s_nop 0
	ds_read_b128 a[16:19], v93
	ds_read_b128 a[20:23], v91
	ds_read_b128 a[24:27], v84 offset:49152
	ds_read_b128 a[28:31], v84 offset:53248
	s_waitcnt lgkmcnt(4)
	v_mfma_f32_32x32x16_bf16 v[48:63], a[0:3], a[8:11], v[48:63]
	s_nop 0
	v_readfirstlane_b32 s53, v118
	v_readfirstlane_b32 s54, v119
	v_mfma_f32_32x32x16_bf16 v[32:47], a[4:7], a[8:11], v[32:47]
	s_and_b32 m0, s32, 7
	s_lshl_b32 m0, m0, 12
	s_add_i32 m0, m0, 0x400
	s_nop 0
	global_load_lds_dwordx4 v[172:173], off
	v_mfma_f32_32x32x16_bf16 v[16:31], a[0:3], a[12:15], v[16:31]
	v_mfma_f32_32x32x16_bf16 v[0:15], a[4:7], a[12:15], v[0:15]
	s_and_b32 m0, s32, 7
	s_lshl_b32 m0, m0, 12
	s_add_i32 m0, m0, 0x800
	s_nop 0
	global_load_lds_dwordx4 v[174:175], off
	s_nop 0
	s_nop 0
	s_nop 0
	s_nop 0
	ds_read_b128 a[0:3], v95
	ds_read_b128 a[4:7], v94
	ds_read_b128 a[8:11], v86 offset:49152
	ds_read_b128 a[12:15], v86 offset:53248
	s_waitcnt lgkmcnt(5)
	v_mfma_f32_32x32x16_bf16 v[48:63], a[16:19], a[24:27], v[48:63]
	v_mfma_f32_32x32x16_bf16 v[32:47], a[20:23], a[24:27], v[32:47]
	s_and_b32 m0, s32, 7
	s_lshl_b32 m0, m0, 12
	s_add_i32 m0, m0, 0xc00
	s_nop 0
	global_load_lds_dwordx4 v[176:177], off
	s_waitcnt lgkmcnt(4)
	v_mfma_f32_32x32x16_bf16 v[16:31], a[16:19], a[28:31], v[16:31]
	v_mfma_f32_32x32x16_bf16 v[0:15], a[20:23], a[28:31], v[0:15]
	s_and_b32 m0, s32, 7
	s_lshl_b32 m0, m0, 11
	s_add_i32 m0, m0, 0x8000
	s_nop 0
	global_load_lds_dwordx4 v[178:179], off
	s_nop 0
	s_nop 0
	s_nop 0
	s_nop 0
	ds_read_b128 a[16:19], v97
	ds_read_b128 a[20:23], v96
	ds_read_b128 a[24:27], v88 offset:49152
	ds_read_b128 a[28:31], v88 offset:53248
	s_waitcnt lgkmcnt(5)
	v_mfma_f32_32x32x16_bf16 v[48:63], a[0:3], a[8:11], v[48:63]
	v_mfma_f32_32x32x16_bf16 v[32:47], a[4:7], a[8:11], v[32:47]
	s_and_b32 m0, s32, 7
	s_lshl_b32 m0, m0, 11
	s_add_i32 m0, m0, 0x8400
	s_nop 0
	global_load_lds_dwordx4 v[180:181], off
	s_waitcnt lgkmcnt(4)
	v_mfma_f32_32x32x16_bf16 v[16:31], a[0:3], a[12:15], v[16:31]
	v_mfma_f32_32x32x16_bf16 v[0:15], a[4:7], a[12:15], v[0:15]
	s_nop 0
	s_nop 0
	s_nop 0
	s_nop 0
	s_waitcnt lgkmcnt(1)
	v_mfma_f32_32x32x16_bf16 v[48:63], a[16:19], a[24:27], v[48:63]
	v_mfma_f32_32x32x16_bf16 v[32:47], a[20:23], a[24:27], v[32:47]
	s_waitcnt vmcnt(6)
	s_waitcnt lgkmcnt(0)
	s_barrier
	ds_read_b128 a[12:15], v101
	ds_read_b128 a[8:11], v100
	ds_read_b128 a[4:7], v99
	ds_read_b128 a[0:3], v98
	v_mfma_f32_32x32x16_bf16 v[16:31], a[16:19], a[28:31], v[16:31]
	v_lshl_add_u64 v[158:159], v[66:67], 0, s[30:31]
	s_nop 0
	v_lshl_add_u64 v[160:161], v[68:69], 0, s[30:31]
	s_nop 0
	v_readfirstlane_b32 s33, v121
	s_nop 0
	v_lshl_add_u64 v[162:163], v[70:71], 0, s[30:31]
	s_nop 0
	v_mfma_f32_32x32x16_bf16 v[0:15], a[20:23], a[28:31], v[0:15]
	s_and_b32 m0, s32, 7
	s_lshl_b32 m0, m0, 12
	s_add_i32 m0, m0, 0xc000
	s_nop 0
	global_load_lds_dwordx4 v[158:159], off
	s_nop 0
	v_lshl_add_u64 v[164:165], v[72:73], 0, s[30:31]
	s_nop 0
	v_readfirstlane_b32 s34, v122
	s_nop 0
	v_lshl_add_u64 v[166:167], v[74:75], 0, s[30:31]
	s_nop 0
	v_readfirstlane_b32 s35, v123
	s_nop 0
	v_lshl_add_u64 v[168:169], v[76:77], 0, s[30:31]
	s_nop 0
	s_mov_b64 s[30:31], 0x400
	s_nop 0
	s_nop 0
	s_nop 0
	s_nop 0
	s_nop 0
	ds_read_b128 a[16:19], v102
	ds_read_b128 a[20:23], v103
	ds_read_b128 a[24:27], v104
	ds_read_b128 a[28:31], v105
	s_waitcnt lgkmcnt(4)
	v_mfma_f32_32x32x16_bf16 v[48:63], a[0:3], a[8:11], v[48:63]
	s_nop 0
	v_readfirstlane_b32 s1, v126
	v_readfirstlane_b32 s36, v124
	v_readfirstlane_b32 s37, v125
	v_mfma_f32_32x32x16_bf16 v[32:47], a[4:7], a[8:11], v[32:47]
	s_and_b32 m0, s32, 7
	s_lshl_b32 m0, m0, 12
	s_add_i32 m0, m0, 0xc400
	s_nop 0
	global_load_lds_dwordx4 v[160:161], off
	v_mfma_f32_32x32x16_bf16 v[16:31], a[0:3], a[12:15], v[16:31]
	v_mfma_f32_32x32x16_bf16 v[0:15], a[4:7], a[12:15], v[0:15]
	s_and_b32 m0, s32, 7
	s_lshl_b32 m0, m0, 12
	s_add_i32 m0, m0, 0xc800
	s_nop 0
	global_load_lds_dwordx4 v[162:163], off
	s_nop 0
	s_nop 0
	s_nop 0
	s_nop 0
	ds_read_b128 a[0:3], v106
	ds_read_b128 a[4:7], v107
	ds_read_b128 a[8:11], v108
	ds_read_b128 a[12:15], v109
	s_waitcnt lgkmcnt(5)
	v_mfma_f32_32x32x16_bf16 v[48:63], a[16:19], a[24:27], v[48:63]
	v_mfma_f32_32x32x16_bf16 v[32:47], a[20:23], a[24:27], v[32:47]
	s_and_b32 m0, s32, 7
	s_lshl_b32 m0, m0, 12
	s_add_i32 m0, m0, 0xcc00
	s_nop 0
	global_load_lds_dwordx4 v[164:165], off
	s_waitcnt lgkmcnt(4)
	v_mfma_f32_32x32x16_bf16 v[16:31], a[16:19], a[28:31], v[16:31]
	v_mfma_f32_32x32x16_bf16 v[0:15], a[20:23], a[28:31], v[0:15]
	s_and_b32 m0, s32, 7
	s_lshl_b32 m0, m0, 11
	s_add_i32 m0, m0, 0x14000
	s_nop 0
	global_load_lds_dwordx4 v[166:167], off
	s_nop 0
	s_nop 0
	s_nop 0
	s_nop 0
	ds_read_b128 a[16:19], v110
	ds_read_b128 a[20:23], v111
	ds_read_b128 a[24:27], v112
	ds_read_b128 a[28:31], v113
	s_waitcnt lgkmcnt(5)
	v_mfma_f32_32x32x16_bf16 v[48:63], a[0:3], a[8:11], v[48:63]
	v_mfma_f32_32x32x16_bf16 v[32:47], a[4:7], a[8:11], v[32:47]
	s_and_b32 m0, s32, 7
	s_lshl_b32 m0, m0, 11
	s_add_i32 m0, m0, 0x14400
	s_nop 0
	global_load_lds_dwordx4 v[168:169], off
	s_waitcnt lgkmcnt(4)
	v_mfma_f32_32x32x16_bf16 v[16:31], a[0:3], a[12:15], v[16:31]
	v_mfma_f32_32x32x16_bf16 v[0:15], a[4:7], a[12:15], v[0:15]
	s_nop 0
	s_nop 0
	s_nop 0
	s_nop 0
	s_waitcnt lgkmcnt(1)
	v_mfma_f32_32x32x16_bf16 v[48:63], a[16:19], a[24:27], v[48:63]
	v_mfma_f32_32x32x16_bf16 v[32:47], a[20:23], a[24:27], v[32:47]
	s_waitcnt vmcnt(6)
	s_waitcnt lgkmcnt(0)
	s_barrier
	ds_read_b128 a[12:15], v82 offset:4096
	ds_read_b128 a[8:11], v82
	ds_read_b128 a[4:7], v83 offset:36864
	ds_read_b128 a[0:3], v83 offset:32768
	v_mfma_f32_32x32x16_bf16 v[16:31], a[16:19], a[28:31], v[16:31]
	v_lshl_add_u64 v[170:171], v[66:67], 0, s[30:31]
	s_nop 0
	v_lshl_add_u64 v[172:173], v[68:69], 0, s[30:31]
	s_nop 0
	v_readfirstlane_b32 s20, v127
	s_nop 0
	v_lshl_add_u64 v[174:175], v[70:71], 0, s[30:31]
	s_nop 0
	v_mfma_f32_32x32x16_bf16 v[0:15], a[20:23], a[28:31], v[0:15]
	s_and_b32 m0, s32, 7
	s_lshl_b32 m0, m0, 12
	s_add_i32 m0, m0, 0x18000
	s_nop 0
	global_load_lds_dwordx4 v[170:171], off
	s_nop 0
	v_lshl_add_u64 v[176:177], v[72:73], 0, s[30:31]
	s_nop 0
	v_readfirstlane_b32 s21, v128
	s_nop 0
	v_lshl_add_u64 v[178:179], v[74:75], 0, s[30:31]
	s_nop 0
	v_readfirstlane_b32 s23, v129
	s_nop 0
	v_lshl_add_u64 v[180:181], v[76:77], 0, s[30:31]
	s_nop 0
	s_mov_b64 s[28:29], 0x480
	s_nop 0
	s_nop 0
	s_nop 0
	s_nop 0
	s_nop 0
	ds_read_b128 a[16:19], v85 offset:32768
	ds_read_b128 a[20:23], v85 offset:36864
	ds_read_b128 a[24:27], v84
	ds_read_b128 a[28:31], v84 offset:4096
	s_waitcnt lgkmcnt(4)
	v_mfma_f32_32x32x16_bf16 v[48:63], a[0:3], a[8:11], v[48:63]
	s_nop 0
	v_lshl_add_u64 v[162:163], v[70:71], 0, s[28:29]
	v_readfirstlane_b32 s24, v131
	s_mov_b64 s[30:31], 0x500
	v_mfma_f32_32x32x16_bf16 v[32:47], a[4:7], a[8:11], v[32:47]
	s_and_b32 m0, s32, 7
	s_lshl_b32 m0, m0, 12
	s_add_i32 m0, m0, 0x18400
	s_nop 0
	global_load_lds_dwordx4 v[172:173], off
	v_mfma_f32_32x32x16_bf16 v[16:31], a[0:3], a[12:15], v[16:31]
	v_mfma_f32_32x32x16_bf16 v[0:15], a[4:7], a[12:15], v[0:15]
	s_and_b32 m0, s32, 7
	s_lshl_b32 m0, m0, 12
	s_add_i32 m0, m0, 0x18800
	s_nop 0
	global_load_lds_dwordx4 v[174:175], off
	s_nop 0
	s_nop 0
	s_nop 0
	s_nop 0
	ds_read_b128 a[0:3], v87 offset:32768
	ds_read_b128 a[4:7], v87 offset:36864
	ds_read_b128 a[8:11], v86
	ds_read_b128 a[12:15], v86 offset:4096
	s_waitcnt lgkmcnt(5)
	v_mfma_f32_32x32x16_bf16 v[48:63], a[16:19], a[24:27], v[48:63]
	v_mfma_f32_32x32x16_bf16 v[32:47], a[20:23], a[24:27], v[32:47]
	s_and_b32 m0, s32, 7
	s_lshl_b32 m0, m0, 12
	s_add_i32 m0, m0, 0x18c00
	s_nop 0
	global_load_lds_dwordx4 v[176:177], off
	s_waitcnt lgkmcnt(4)
	v_mfma_f32_32x32x16_bf16 v[16:31], a[16:19], a[28:31], v[16:31]
	v_mfma_f32_32x32x16_bf16 v[0:15], a[20:23], a[28:31], v[0:15]
	s_and_b32 m0, s32, 7
	s_lshl_b32 m0, m0, 11
	s_add_i32 m0, m0, 0x20000
	s_nop 0
	global_load_lds_dwordx4 v[178:179], off
	s_nop 0
	s_nop 0
	s_nop 0
	s_nop 0
	ds_read_b128 a[16:19], v89 offset:32768
	ds_read_b128 a[20:23], v89 offset:36864
	ds_read_b128 a[24:27], v88
	ds_read_b128 a[28:31], v88 offset:4096
	s_waitcnt lgkmcnt(5)
	v_mfma_f32_32x32x16_bf16 v[48:63], a[0:3], a[8:11], v[48:63]
	v_mfma_f32_32x32x16_bf16 v[32:47], a[4:7], a[8:11], v[32:47]
	s_and_b32 m0, s32, 7
	s_lshl_b32 m0, m0, 11
	s_add_i32 m0, m0, 0x20400
	s_nop 0
	global_load_lds_dwordx4 v[180:181], off
	s_waitcnt lgkmcnt(4)
	v_mfma_f32_32x32x16_bf16 v[16:31], a[0:3], a[12:15], v[16:31]
	v_mfma_f32_32x32x16_bf16 v[0:15], a[4:7], a[12:15], v[0:15]
	s_nop 0
	s_nop 0
	s_nop 0
	s_nop 0
	s_waitcnt lgkmcnt(1)
	v_mfma_f32_32x32x16_bf16 v[48:63], a[16:19], a[24:27], v[48:63]
	v_mfma_f32_32x32x16_bf16 v[32:47], a[20:23], a[24:27], v[32:47]
	s_waitcnt vmcnt(6)
	s_waitcnt lgkmcnt(0)
	s_barrier
	ds_read_b128 a[12:15], v82 offset:53248
	ds_read_b128 a[8:11], v82 offset:49152
	ds_read_b128 a[4:7], v90
	ds_read_b128 a[0:3], v92
	v_mfma_f32_32x32x16_bf16 v[16:31], a[16:19], a[28:31], v[16:31]
	v_lshl_add_u64 v[158:159], v[66:67], 0, s[28:29]
	s_nop 0
	v_lshl_add_u64 v[160:161], v[68:69], 0, s[28:29]
	s_nop 0
	s_nop 0
	s_nop 0
	s_nop 0
	v_mfma_f32_32x32x16_bf16 v[0:15], a[20:23], a[28:31], v[0:15]
	s_and_b32 m0, s32, 7
	s_lshl_b32 m0, m0, 12
	s_add_i32 m0, m0, 0x0
	s_nop 0
	global_load_lds_dwordx4 v[158:159], off
	s_nop 0
	v_lshl_add_u64 v[164:165], v[72:73], 0, s[28:29]
	s_nop 0
	s_nop 0
	s_nop 0
	v_lshl_add_u64 v[166:167], v[74:75], 0, s[28:29]
	s_nop 0
	s_nop 0
	s_nop 0
	v_lshl_add_u64 v[168:169], v[76:77], 0, s[28:29]
	v_readfirstlane_b32 s28, v130
	s_nop 0
	v_readfirstlane_b32 s29, v120
	s_nop 0
	s_nop 0
	s_nop 0
	s_nop 0
	s_nop 0
	ds_read_b128 a[16:19], v93
	ds_read_b128 a[20:23], v91
	ds_read_b128 a[24:27], v84 offset:49152
	ds_read_b128 a[28:31], v84 offset:53248
	s_waitcnt lgkmcnt(4)
	v_mfma_f32_32x32x16_bf16 v[48:63], a[0:3], a[8:11], v[48:63]
	s_nop 0
	v_lshl_add_u64 v[174:175], v[70:71], 0, s[30:31]
	v_mfma_f32_32x32x16_bf16 v[32:47], a[4:7], a[8:11], v[32:47]
	s_and_b32 m0, s32, 7
	s_lshl_b32 m0, m0, 12
	s_add_i32 m0, m0, 0x400
	s_nop 0
	global_load_lds_dwordx4 v[160:161], off
	v_mfma_f32_32x32x16_bf16 v[16:31], a[0:3], a[12:15], v[16:31]
	v_mfma_f32_32x32x16_bf16 v[0:15], a[4:7], a[12:15], v[0:15]
	s_and_b32 m0, s32, 7
	s_lshl_b32 m0, m0, 12
	s_add_i32 m0, m0, 0x800
	s_nop 0
	global_load_lds_dwordx4 v[162:163], off
	s_nop 0
	s_nop 0
	s_nop 0
	s_nop 0
	ds_read_b128 a[0:3], v95
	ds_read_b128 a[4:7], v94
	ds_read_b128 a[8:11], v86 offset:49152
	ds_read_b128 a[12:15], v86 offset:53248
	s_waitcnt lgkmcnt(5)
	v_mfma_f32_32x32x16_bf16 v[48:63], a[16:19], a[24:27], v[48:63]
	v_mfma_f32_32x32x16_bf16 v[32:47], a[20:23], a[24:27], v[32:47]
	s_and_b32 m0, s32, 7
	s_lshl_b32 m0, m0, 12
	s_add_i32 m0, m0, 0xc00
	s_nop 0
	global_load_lds_dwordx4 v[164:165], off
	s_waitcnt lgkmcnt(4)
	v_mfma_f32_32x32x16_bf16 v[16:31], a[16:19], a[28:31], v[16:31]
	v_mfma_f32_32x32x16_bf16 v[0:15], a[20:23], a[28:31], v[0:15]
	s_and_b32 m0, s32, 7
	s_lshl_b32 m0, m0, 11
	s_add_i32 m0, m0, 0x8000
	s_nop 0
	global_load_lds_dwordx4 v[166:167], off
	s_nop 0
	s_nop 0
	s_nop 0
	s_nop 0
	ds_read_b128 a[16:19], v97
	ds_read_b128 a[20:23], v96
	ds_read_b128 a[24:27], v88 offset:49152
	ds_read_b128 a[28:31], v88 offset:53248
	s_waitcnt lgkmcnt(5)
	v_mfma_f32_32x32x16_bf16 v[48:63], a[0:3], a[8:11], v[48:63]
	v_mfma_f32_32x32x16_bf16 v[32:47], a[4:7], a[8:11], v[32:47]
	s_and_b32 m0, s32, 7
	s_lshl_b32 m0, m0, 11
	s_add_i32 m0, m0, 0x8400
	s_nop 0
	global_load_lds_dwordx4 v[168:169], off
	s_waitcnt lgkmcnt(4)
	v_mfma_f32_32x32x16_bf16 v[16:31], a[0:3], a[12:15], v[16:31]
	v_mfma_f32_32x32x16_bf16 v[0:15], a[4:7], a[12:15], v[0:15]
	s_nop 0
	s_nop 0
	s_nop 0
	s_nop 0
	s_waitcnt lgkmcnt(1)
	v_mfma_f32_32x32x16_bf16 v[48:63], a[16:19], a[24:27], v[48:63]
	v_mfma_f32_32x32x16_bf16 v[32:47], a[20:23], a[24:27], v[32:47]
	s_waitcnt vmcnt(6)
	s_waitcnt lgkmcnt(0)
	s_barrier
	ds_read_b128 a[12:15], v101
	ds_read_b128 a[8:11], v100
	ds_read_b128 a[4:7], v99
	ds_read_b128 a[0:3], v98
	v_mfma_f32_32x32x16_bf16 v[16:31], a[16:19], a[28:31], v[16:31]
	v_lshl_add_u64 v[170:171], v[66:67], 0, s[30:31]
	s_nop 0
	v_lshl_add_u64 v[172:173], v[68:69], 0, s[30:31]
	s_nop 0
	s_nop 0
	s_nop 0
	s_nop 0
	v_mfma_f32_32x32x16_bf16 v[0:15], a[20:23], a[28:31], v[0:15]
	s_and_b32 m0, s32, 7
	s_lshl_b32 m0, m0, 12
	s_add_i32 m0, m0, 0xc000
	s_nop 0
	global_load_lds_dwordx4 v[170:171], off
	s_nop 0
	v_lshl_add_u64 v[176:177], v[72:73], 0, s[30:31]
	s_nop 0
	s_nop 0
	s_nop 0
	v_lshl_add_u64 v[178:179], v[74:75], 0, s[30:31]
	s_nop 0
	s_nop 0
	s_nop 0
	v_lshl_add_u64 v[180:181], v[76:77], 0, s[30:31]
	s_nop 0
	s_mov_b64 s[30:31], 0x580
	s_nop 0
	s_nop 0
	s_nop 0
	s_nop 0
	s_nop 0
	ds_read_b128 a[16:19], v102
	ds_read_b128 a[20:23], v103
	ds_read_b128 a[24:27], v104
	ds_read_b128 a[28:31], v105
	s_waitcnt lgkmcnt(4)
	v_mfma_f32_32x32x16_bf16 v[48:63], a[0:3], a[8:11], v[48:63]
	s_nop 0
	v_lshl_add_u64 v[162:163], v[70:71], 0, s[30:31]
	v_mfma_f32_32x32x16_bf16 v[32:47], a[4:7], a[8:11], v[32:47]
	s_and_b32 m0, s32, 7
	s_lshl_b32 m0, m0, 12
	s_add_i32 m0, m0, 0xc400
	s_nop 0
	global_load_lds_dwordx4 v[172:173], off
	v_mfma_f32_32x32x16_bf16 v[16:31], a[0:3], a[12:15], v[16:31]
	v_mfma_f32_32x32x16_bf16 v[0:15], a[4:7], a[12:15], v[0:15]
	s_and_b32 m0, s32, 7
	s_lshl_b32 m0, m0, 12
	s_add_i32 m0, m0, 0xc800
	s_nop 0
	global_load_lds_dwordx4 v[174:175], off
	s_nop 0
	s_nop 0
	s_nop 0
	s_nop 0
	ds_read_b128 a[0:3], v106
	ds_read_b128 a[4:7], v107
	ds_read_b128 a[8:11], v108
	ds_read_b128 a[12:15], v109
	s_waitcnt lgkmcnt(5)
	v_mfma_f32_32x32x16_bf16 v[48:63], a[16:19], a[24:27], v[48:63]
	v_mfma_f32_32x32x16_bf16 v[32:47], a[20:23], a[24:27], v[32:47]
	s_and_b32 m0, s32, 7
	s_lshl_b32 m0, m0, 12
	s_add_i32 m0, m0, 0xcc00
	s_nop 0
	global_load_lds_dwordx4 v[176:177], off
	s_waitcnt lgkmcnt(4)
	v_mfma_f32_32x32x16_bf16 v[16:31], a[16:19], a[28:31], v[16:31]
	v_mfma_f32_32x32x16_bf16 v[0:15], a[20:23], a[28:31], v[0:15]
	s_and_b32 m0, s32, 7
	s_lshl_b32 m0, m0, 11
	s_add_i32 m0, m0, 0x14000
	s_nop 0
	global_load_lds_dwordx4 v[178:179], off
	s_nop 0
	s_nop 0
	s_nop 0
	s_nop 0
	ds_read_b128 a[16:19], v110
	ds_read_b128 a[20:23], v111
	ds_read_b128 a[24:27], v112
	ds_read_b128 a[28:31], v113
	s_waitcnt lgkmcnt(5)
	v_mfma_f32_32x32x16_bf16 v[48:63], a[0:3], a[8:11], v[48:63]
	v_mfma_f32_32x32x16_bf16 v[32:47], a[4:7], a[8:11], v[32:47]
	s_and_b32 m0, s32, 7
	s_lshl_b32 m0, m0, 11
	s_add_i32 m0, m0, 0x14400
	s_nop 0
	global_load_lds_dwordx4 v[180:181], off
	s_waitcnt lgkmcnt(4)
	v_mfma_f32_32x32x16_bf16 v[16:31], a[0:3], a[12:15], v[16:31]
	v_mfma_f32_32x32x16_bf16 v[0:15], a[4:7], a[12:15], v[0:15]
	s_nop 0
	s_nop 0
	s_nop 0
	s_nop 0
	s_waitcnt lgkmcnt(1)
	v_mfma_f32_32x32x16_bf16 v[48:63], a[16:19], a[24:27], v[48:63]
	v_mfma_f32_32x32x16_bf16 v[32:47], a[20:23], a[24:27], v[32:47]
	s_waitcnt vmcnt(6)
	s_waitcnt lgkmcnt(0)
	s_barrier
	ds_read_b128 a[12:15], v82 offset:4096
	ds_read_b128 a[8:11], v82
	ds_read_b128 a[4:7], v83 offset:36864
	ds_read_b128 a[0:3], v83 offset:32768
	v_mfma_f32_32x32x16_bf16 v[16:31], a[16:19], a[28:31], v[16:31]
	v_lshl_add_u64 v[158:159], v[66:67], 0, s[30:31]
	s_nop 0
	v_lshl_add_u64 v[160:161], v[68:69], 0, s[30:31]
	s_nop 0
	s_nop 0
	s_nop 0
	s_nop 0
	v_mfma_f32_32x32x16_bf16 v[0:15], a[20:23], a[28:31], v[0:15]
	s_and_b32 m0, s32, 7
	s_lshl_b32 m0, m0, 12
	s_add_i32 m0, m0, 0x18000
	s_nop 0
	global_load_lds_dwordx4 v[158:159], off
	s_nop 0
	v_lshl_add_u64 v[164:165], v[72:73], 0, s[30:31]
	s_nop 0
	s_nop 0
	s_nop 0
	v_lshl_add_u64 v[166:167], v[74:75], 0, s[30:31]
	s_nop 0
	s_nop 0
	s_nop 0
	v_lshl_add_u64 v[168:169], v[76:77], 0, s[30:31]
	s_nop 0
	s_mov_b64 s[30:31], 0x600
	s_nop 0
	s_nop 0
	s_nop 0
	s_nop 0
	s_nop 0
	ds_read_b128 a[16:19], v85 offset:32768
	ds_read_b128 a[20:23], v85 offset:36864
	ds_read_b128 a[24:27], v84
	ds_read_b128 a[28:31], v84 offset:4096
	s_waitcnt lgkmcnt(4)
	v_mfma_f32_32x32x16_bf16 v[48:63], a[0:3], a[8:11], v[48:63]
	s_nop 0
	v_mfma_f32_32x32x16_bf16 v[32:47], a[4:7], a[8:11], v[32:47]
	s_and_b32 m0, s32, 7
	s_lshl_b32 m0, m0, 12
	s_add_i32 m0, m0, 0x18400
	s_nop 0
	global_load_lds_dwordx4 v[160:161], off
	v_mfma_f32_32x32x16_bf16 v[16:31], a[0:3], a[12:15], v[16:31]
	v_mfma_f32_32x32x16_bf16 v[0:15], a[4:7], a[12:15], v[0:15]
	s_and_b32 m0, s32, 7
	s_lshl_b32 m0, m0, 12
	s_add_i32 m0, m0, 0x18800
	s_nop 0
	global_load_lds_dwordx4 v[162:163], off
	s_nop 0
	s_nop 0
	s_nop 0
	s_nop 0
	ds_read_b128 a[0:3], v87 offset:32768
	ds_read_b128 a[4:7], v87 offset:36864
	ds_read_b128 a[8:11], v86
	ds_read_b128 a[12:15], v86 offset:4096
	s_waitcnt lgkmcnt(5)
	v_mfma_f32_32x32x16_bf16 v[48:63], a[16:19], a[24:27], v[48:63]
	v_mfma_f32_32x32x16_bf16 v[32:47], a[20:23], a[24:27], v[32:47]
	s_and_b32 m0, s32, 7
	s_lshl_b32 m0, m0, 12
	s_add_i32 m0, m0, 0x18c00
	s_nop 0
	global_load_lds_dwordx4 v[164:165], off
	s_waitcnt lgkmcnt(4)
	v_mfma_f32_32x32x16_bf16 v[16:31], a[16:19], a[28:31], v[16:31]
	v_mfma_f32_32x32x16_bf16 v[0:15], a[20:23], a[28:31], v[0:15]
	s_and_b32 m0, s32, 7
	s_lshl_b32 m0, m0, 11
	s_add_i32 m0, m0, 0x20000
	s_nop 0
	global_load_lds_dwordx4 v[166:167], off
	s_nop 0
	s_nop 0
	s_nop 0
	s_nop 0
	ds_read_b128 a[16:19], v89 offset:32768
	ds_read_b128 a[20:23], v89 offset:36864
	ds_read_b128 a[24:27], v88
	ds_read_b128 a[28:31], v88 offset:4096
	s_waitcnt lgkmcnt(5)
	v_mfma_f32_32x32x16_bf16 v[48:63], a[0:3], a[8:11], v[48:63]
	v_mfma_f32_32x32x16_bf16 v[32:47], a[4:7], a[8:11], v[32:47]
	s_and_b32 m0, s32, 7
	s_lshl_b32 m0, m0, 11
	s_add_i32 m0, m0, 0x20400
	s_nop 0
	global_load_lds_dwordx4 v[168:169], off
	s_waitcnt lgkmcnt(4)
	v_mfma_f32_32x32x16_bf16 v[16:31], a[0:3], a[12:15], v[16:31]
	v_mfma_f32_32x32x16_bf16 v[0:15], a[4:7], a[12:15], v[0:15]
	s_nop 0
	s_nop 0
	s_nop 0
	s_nop 0
	s_waitcnt lgkmcnt(1)
	v_mfma_f32_32x32x16_bf16 v[48:63], a[16:19], a[24:27], v[48:63]
	v_mfma_f32_32x32x16_bf16 v[32:47], a[20:23], a[24:27], v[32:47]
	s_waitcnt vmcnt(6)
	s_waitcnt lgkmcnt(0)
	s_barrier
	ds_read_b128 a[12:15], v82 offset:53248
	ds_read_b128 a[8:11], v82 offset:49152
	ds_read_b128 a[4:7], v90
	ds_read_b128 a[0:3], v92
	v_mfma_f32_32x32x16_bf16 v[16:31], a[16:19], a[28:31], v[16:31]
	v_lshl_add_u64 v[170:171], v[66:67], 0, s[30:31]
	s_nop 0
	v_lshl_add_u64 v[172:173], v[68:69], 0, s[30:31]
	s_nop 0
	s_nop 0
	s_nop 0
	v_lshl_add_u64 v[174:175], v[70:71], 0, s[30:31]
	s_nop 0
	v_mfma_f32_32x32x16_bf16 v[0:15], a[20:23], a[28:31], v[0:15]
	s_and_b32 m0, s32, 7
	s_lshl_b32 m0, m0, 12
	s_add_i32 m0, m0, 0x0
	s_nop 0
	global_load_lds_dwordx4 v[170:171], off
	s_nop 0
	v_lshl_add_u64 v[176:177], v[72:73], 0, s[30:31]
	s_nop 0
	s_nop 0
	s_nop 0
	v_lshl_add_u64 v[178:179], v[74:75], 0, s[30:31]
	s_nop 0
	s_nop 0
	s_nop 0
	v_lshl_add_u64 v[180:181], v[76:77], 0, s[30:31]
	s_nop 0
	s_mov_b64 s[30:31], 0x680
	s_nop 0
	s_nop 0
	s_nop 0
	s_nop 0
	s_nop 0
	ds_read_b128 a[16:19], v93
	ds_read_b128 a[20:23], v91
	ds_read_b128 a[24:27], v84 offset:49152
	ds_read_b128 a[28:31], v84 offset:53248
	s_waitcnt lgkmcnt(4)
	v_mfma_f32_32x32x16_bf16 v[48:63], a[0:3], a[8:11], v[48:63]
	s_nop 0
	v_mfma_f32_32x32x16_bf16 v[32:47], a[4:7], a[8:11], v[32:47]
	s_and_b32 m0, s32, 7
	s_lshl_b32 m0, m0, 12
	s_add_i32 m0, m0, 0x400
	s_nop 0
	global_load_lds_dwordx4 v[172:173], off
	v_mfma_f32_32x32x16_bf16 v[16:31], a[0:3], a[12:15], v[16:31]
	v_mfma_f32_32x32x16_bf16 v[0:15], a[4:7], a[12:15], v[0:15]
	s_and_b32 m0, s32, 7
	s_lshl_b32 m0, m0, 12
	s_add_i32 m0, m0, 0x800
	s_nop 0
	global_load_lds_dwordx4 v[174:175], off
	s_nop 0
	s_nop 0
	s_nop 0
	s_nop 0
	ds_read_b128 a[0:3], v95
	ds_read_b128 a[4:7], v94
	ds_read_b128 a[8:11], v86 offset:49152
	ds_read_b128 a[12:15], v86 offset:53248
	s_waitcnt lgkmcnt(5)
	v_mfma_f32_32x32x16_bf16 v[48:63], a[16:19], a[24:27], v[48:63]
	v_mfma_f32_32x32x16_bf16 v[32:47], a[20:23], a[24:27], v[32:47]
	s_and_b32 m0, s32, 7
	s_lshl_b32 m0, m0, 12
	s_add_i32 m0, m0, 0xc00
	s_nop 0
	global_load_lds_dwordx4 v[176:177], off
	s_waitcnt lgkmcnt(4)
	v_mfma_f32_32x32x16_bf16 v[16:31], a[16:19], a[28:31], v[16:31]
	v_mfma_f32_32x32x16_bf16 v[0:15], a[20:23], a[28:31], v[0:15]
	s_and_b32 m0, s32, 7
	s_lshl_b32 m0, m0, 11
	s_add_i32 m0, m0, 0x8000
	s_nop 0
	global_load_lds_dwordx4 v[178:179], off
	s_nop 0
	s_nop 0
	s_nop 0
	s_nop 0
	ds_read_b128 a[16:19], v97
	ds_read_b128 a[20:23], v96
	ds_read_b128 a[24:27], v88 offset:49152
	ds_read_b128 a[28:31], v88 offset:53248
	s_waitcnt lgkmcnt(5)
	v_mfma_f32_32x32x16_bf16 v[48:63], a[0:3], a[8:11], v[48:63]
	v_mfma_f32_32x32x16_bf16 v[32:47], a[4:7], a[8:11], v[32:47]
	s_and_b32 m0, s32, 7
	s_lshl_b32 m0, m0, 11
	s_add_i32 m0, m0, 0x8400
	s_nop 0
	global_load_lds_dwordx4 v[180:181], off
	s_waitcnt lgkmcnt(4)
	v_mfma_f32_32x32x16_bf16 v[16:31], a[0:3], a[12:15], v[16:31]
	v_mfma_f32_32x32x16_bf16 v[0:15], a[4:7], a[12:15], v[0:15]
	s_nop 0
	s_nop 0
	s_nop 0
	s_nop 0
	s_waitcnt lgkmcnt(1)
	v_mfma_f32_32x32x16_bf16 v[48:63], a[16:19], a[24:27], v[48:63]
	v_mfma_f32_32x32x16_bf16 v[32:47], a[20:23], a[24:27], v[32:47]
	s_waitcnt vmcnt(6)
	s_waitcnt lgkmcnt(0)
	s_barrier
	ds_read_b128 a[12:15], v101
	ds_read_b128 a[8:11], v100
	ds_read_b128 a[4:7], v99
	ds_read_b128 a[0:3], v98
	v_mfma_f32_32x32x16_bf16 v[16:31], a[16:19], a[28:31], v[16:31]
	v_lshl_add_u64 v[158:159], v[66:67], 0, s[30:31]
	s_nop 0
	v_lshl_add_u64 v[160:161], v[68:69], 0, s[30:31]
	s_nop 0
	s_nop 0
	s_nop 0
	v_lshl_add_u64 v[162:163], v[70:71], 0, s[30:31]
	s_nop 0
	v_mfma_f32_32x32x16_bf16 v[0:15], a[20:23], a[28:31], v[0:15]
	s_and_b32 m0, s32, 7
	s_lshl_b32 m0, m0, 12
	s_add_i32 m0, m0, 0xc000
	s_nop 0
	global_load_lds_dwordx4 v[158:159], off
	s_nop 0
	v_lshl_add_u64 v[164:165], v[72:73], 0, s[30:31]
	s_nop 0
	s_nop 0
	s_nop 0
	v_lshl_add_u64 v[166:167], v[74:75], 0, s[30:31]
	s_nop 0
	s_nop 0
	s_nop 0
	v_lshl_add_u64 v[168:169], v[76:77], 0, s[30:31]
	s_nop 0
	s_mov_b64 s[30:31], 0x700
	s_nop 0
	s_nop 0
	s_nop 0
	s_nop 0
	s_nop 0
	ds_read_b128 a[16:19], v102
	ds_read_b128 a[20:23], v103
	ds_read_b128 a[24:27], v104
	ds_read_b128 a[28:31], v105
	s_waitcnt lgkmcnt(4)
	v_mfma_f32_32x32x16_bf16 v[48:63], a[0:3], a[8:11], v[48:63]
	s_nop 0
	v_mfma_f32_32x32x16_bf16 v[32:47], a[4:7], a[8:11], v[32:47]
	s_and_b32 m0, s32, 7
	s_lshl_b32 m0, m0, 12
	s_add_i32 m0, m0, 0xc400
	s_nop 0
	global_load_lds_dwordx4 v[160:161], off
	v_mfma_f32_32x32x16_bf16 v[16:31], a[0:3], a[12:15], v[16:31]
	v_mfma_f32_32x32x16_bf16 v[0:15], a[4:7], a[12:15], v[0:15]
	s_and_b32 m0, s32, 7
	s_lshl_b32 m0, m0, 12
	s_add_i32 m0, m0, 0xc800
	s_nop 0
	global_load_lds_dwordx4 v[162:163], off
	s_nop 0
	s_nop 0
	s_nop 0
	s_nop 0
	ds_read_b128 a[0:3], v106
	ds_read_b128 a[4:7], v107
	ds_read_b128 a[8:11], v108
	ds_read_b128 a[12:15], v109
	s_waitcnt lgkmcnt(5)
	v_mfma_f32_32x32x16_bf16 v[48:63], a[16:19], a[24:27], v[48:63]
	v_mfma_f32_32x32x16_bf16 v[32:47], a[20:23], a[24:27], v[32:47]
	s_and_b32 m0, s32, 7
	s_lshl_b32 m0, m0, 12
	s_add_i32 m0, m0, 0xcc00
	s_nop 0
	global_load_lds_dwordx4 v[164:165], off
	s_waitcnt lgkmcnt(4)
	v_mfma_f32_32x32x16_bf16 v[16:31], a[16:19], a[28:31], v[16:31]
	v_mfma_f32_32x32x16_bf16 v[0:15], a[20:23], a[28:31], v[0:15]
	s_and_b32 m0, s32, 7
	s_lshl_b32 m0, m0, 11
	s_add_i32 m0, m0, 0x14000
	s_nop 0
	global_load_lds_dwordx4 v[166:167], off
	s_nop 0
	s_nop 0
	s_nop 0
	s_nop 0
	ds_read_b128 a[16:19], v110
	ds_read_b128 a[20:23], v111
	ds_read_b128 a[24:27], v112
	ds_read_b128 a[28:31], v113
	s_waitcnt lgkmcnt(5)
	v_mfma_f32_32x32x16_bf16 v[48:63], a[0:3], a[8:11], v[48:63]
	v_mfma_f32_32x32x16_bf16 v[32:47], a[4:7], a[8:11], v[32:47]
	s_and_b32 m0, s32, 7
	s_lshl_b32 m0, m0, 11
	s_add_i32 m0, m0, 0x14400
	s_nop 0
	global_load_lds_dwordx4 v[168:169], off
	s_waitcnt lgkmcnt(4)
	v_mfma_f32_32x32x16_bf16 v[16:31], a[0:3], a[12:15], v[16:31]
	v_mfma_f32_32x32x16_bf16 v[0:15], a[4:7], a[12:15], v[0:15]
	s_nop 0
	s_nop 0
	s_nop 0
	s_nop 0
	s_waitcnt lgkmcnt(1)
	v_mfma_f32_32x32x16_bf16 v[48:63], a[16:19], a[24:27], v[48:63]
	v_mfma_f32_32x32x16_bf16 v[32:47], a[20:23], a[24:27], v[32:47]
	s_waitcnt vmcnt(6)
	s_waitcnt lgkmcnt(0)
	s_barrier
	ds_read_b128 a[12:15], v82 offset:4096
	ds_read_b128 a[8:11], v82
	ds_read_b128 a[4:7], v83 offset:36864
	ds_read_b128 a[0:3], v83 offset:32768
	v_mfma_f32_32x32x16_bf16 v[16:31], a[16:19], a[28:31], v[16:31]
	v_lshl_add_u64 v[170:171], v[66:67], 0, s[30:31]
	s_nop 0
	v_lshl_add_u64 v[172:173], v[68:69], 0, s[30:31]
	s_nop 0
	s_nop 0
	s_nop 0
	v_lshl_add_u64 v[174:175], v[70:71], 0, s[30:31]
	s_nop 0
	v_mfma_f32_32x32x16_bf16 v[0:15], a[20:23], a[28:31], v[0:15]
	s_and_b32 m0, s32, 7
	s_lshl_b32 m0, m0, 12
	s_add_i32 m0, m0, 0x18000
	s_nop 0
	global_load_lds_dwordx4 v[170:171], off
	s_nop 0
	v_lshl_add_u64 v[176:177], v[72:73], 0, s[30:31]
	s_nop 0
	s_nop 0
	s_nop 0
	v_lshl_add_u64 v[178:179], v[74:75], 0, s[30:31]
	s_nop 0
	s_nop 0
	s_nop 0
	v_lshl_add_u64 v[180:181], v[76:77], 0, s[30:31]
	s_nop 0
	s_mov_b64 s[30:31], 0x780
	s_nop 0
	s_nop 0
	s_nop 0
	s_nop 0
	s_nop 0
	ds_read_b128 a[16:19], v85 offset:32768
	ds_read_b128 a[20:23], v85 offset:36864
	ds_read_b128 a[24:27], v84
	ds_read_b128 a[28:31], v84 offset:4096
	s_waitcnt lgkmcnt(4)
	v_mfma_f32_32x32x16_bf16 v[48:63], a[0:3], a[8:11], v[48:63]
	v_lshl_add_u64 v[158:159], v[66:67], 0, s[30:31]
	s_nop 0
	v_mfma_f32_32x32x16_bf16 v[32:47], a[4:7], a[8:11], v[32:47]
	s_and_b32 m0, s32, 7
	s_lshl_b32 m0, m0, 12
	s_add_i32 m0, m0, 0x18400
	s_nop 0
	global_load_lds_dwordx4 v[172:173], off
	v_mfma_f32_32x32x16_bf16 v[16:31], a[0:3], a[12:15], v[16:31]
	v_mfma_f32_32x32x16_bf16 v[0:15], a[4:7], a[12:15], v[0:15]
	s_and_b32 m0, s32, 7
	s_lshl_b32 m0, m0, 12
	s_add_i32 m0, m0, 0x18800
	s_nop 0
	global_load_lds_dwordx4 v[174:175], off
	s_nop 0
	s_nop 0
	s_nop 0
	s_nop 0
	ds_read_b128 a[0:3], v87 offset:32768
	ds_read_b128 a[4:7], v87 offset:36864
	ds_read_b128 a[8:11], v86
	ds_read_b128 a[12:15], v86 offset:4096
	s_waitcnt lgkmcnt(5)
	v_mfma_f32_32x32x16_bf16 v[48:63], a[16:19], a[24:27], v[48:63]
	v_mfma_f32_32x32x16_bf16 v[32:47], a[20:23], a[24:27], v[32:47]
	s_and_b32 m0, s32, 7
	s_lshl_b32 m0, m0, 12
	s_add_i32 m0, m0, 0x18c00
	s_nop 0
	global_load_lds_dwordx4 v[176:177], off
	s_waitcnt lgkmcnt(4)
	v_mfma_f32_32x32x16_bf16 v[16:31], a[16:19], a[28:31], v[16:31]
	v_mfma_f32_32x32x16_bf16 v[0:15], a[20:23], a[28:31], v[0:15]
	s_and_b32 m0, s32, 7
	s_lshl_b32 m0, m0, 11
	s_add_i32 m0, m0, 0x20000
	s_nop 0
	global_load_lds_dwordx4 v[178:179], off
	s_nop 0
	s_nop 0
	s_nop 0
	s_nop 0
	ds_read_b128 a[16:19], v89 offset:32768
	ds_read_b128 a[20:23], v89 offset:36864
	ds_read_b128 a[24:27], v88
	ds_read_b128 a[28:31], v88 offset:4096
	s_waitcnt lgkmcnt(5)
	v_mfma_f32_32x32x16_bf16 v[48:63], a[0:3], a[8:11], v[48:63]
	v_mfma_f32_32x32x16_bf16 v[32:47], a[4:7], a[8:11], v[32:47]
	s_and_b32 m0, s32, 7
	s_lshl_b32 m0, m0, 11
	s_add_i32 m0, m0, 0x20400
	s_nop 0
	global_load_lds_dwordx4 v[180:181], off
	s_waitcnt lgkmcnt(4)
	v_mfma_f32_32x32x16_bf16 v[16:31], a[0:3], a[12:15], v[16:31]
	v_mfma_f32_32x32x16_bf16 v[0:15], a[4:7], a[12:15], v[0:15]
	s_nop 0
	s_nop 0
	s_nop 0
	s_nop 0
	s_waitcnt lgkmcnt(1)
	v_mfma_f32_32x32x16_bf16 v[48:63], a[16:19], a[24:27], v[48:63]
	v_mfma_f32_32x32x16_bf16 v[32:47], a[20:23], a[24:27], v[32:47]
	s_waitcnt vmcnt(6)
	s_waitcnt lgkmcnt(0)
	s_barrier
	ds_read_b128 a[12:15], v82 offset:53248
	ds_read_b128 a[8:11], v82 offset:49152
	ds_read_b128 a[4:7], v90
	ds_read_b128 a[0:3], v92
	s_nop 0
	v_lshl_add_u64 v[160:161], v[68:69], 0, s[30:31]
	s_nop 0
	v_mfma_f32_32x32x16_bf16 v[16:31], a[16:19], a[28:31], v[16:31]
	s_nop 0
	v_lshl_add_u64 v[162:163], v[70:71], 0, s[30:31]
	s_nop 0
	v_readlane_b32 s20, v215, 52
	s_nop 0
	v_lshl_add_u64 v[164:165], v[72:73], 0, s[30:31]
	s_nop 0
	v_mfma_f32_32x32x16_bf16 v[0:15], a[20:23], a[28:31], v[0:15]
	s_and_b32 m0, s32, 7
	s_lshl_b32 m0, m0, 12
	s_add_i32 m0, m0, 0x0
	s_nop 0
	global_load_lds_dwordx4 v[158:159], off
	s_nop 0
	v_lshl_add_u64 v[166:167], v[74:75], 0, s[30:31]
	s_nop 0
	v_readlane_b32 s21, v215, 53
	s_nop 0
	v_lshl_add_u64 v[168:169], v[76:77], 0, s[30:31]
	s_nop 0
	s_mov_b32 s23, 0
	s_nop 0
	s_nop 0
	s_nop 0
	s_nop 0
	s_nop 0
	ds_read_b128 a[16:19], v93
	ds_read_b128 a[20:23], v91
	ds_read_b128 a[24:27], v84 offset:49152
	ds_read_b128 a[28:31], v84 offset:53248
	s_waitcnt lgkmcnt(4)
	v_mfma_f32_32x32x16_bf16 v[48:63], a[0:3], a[8:11], v[48:63]
	v_mfma_f32_32x32x16_bf16 v[32:47], a[4:7], a[8:11], v[32:47]
	s_and_b32 m0, s32, 7
	s_lshl_b32 m0, m0, 12
	s_add_i32 m0, m0, 0x400
	s_nop 0
	global_load_lds_dwordx4 v[160:161], off
	v_mfma_f32_32x32x16_bf16 v[16:31], a[0:3], a[12:15], v[16:31]
	v_mfma_f32_32x32x16_bf16 v[0:15], a[4:7], a[12:15], v[0:15]
	s_and_b32 m0, s32, 7
	s_lshl_b32 m0, m0, 12
	s_add_i32 m0, m0, 0x800
	s_nop 0
	global_load_lds_dwordx4 v[162:163], off
	s_nop 0
	s_nop 0
	s_nop 0
	s_nop 0
	ds_read_b128 a[0:3], v95
	ds_read_b128 a[4:7], v94
	ds_read_b128 a[8:11], v86 offset:49152
	ds_read_b128 a[12:15], v86 offset:53248
	s_waitcnt lgkmcnt(5)
	v_mfma_f32_32x32x16_bf16 v[48:63], a[16:19], a[24:27], v[48:63]
	v_mfma_f32_32x32x16_bf16 v[32:47], a[20:23], a[24:27], v[32:47]
	s_and_b32 m0, s32, 7
	s_lshl_b32 m0, m0, 12
	s_add_i32 m0, m0, 0xc00
	s_nop 0
	global_load_lds_dwordx4 v[164:165], off
	s_waitcnt lgkmcnt(4)
	v_mfma_f32_32x32x16_bf16 v[16:31], a[16:19], a[28:31], v[16:31]
	v_mfma_f32_32x32x16_bf16 v[0:15], a[20:23], a[28:31], v[0:15]
	s_and_b32 m0, s32, 7
	s_lshl_b32 m0, m0, 11
	s_add_i32 m0, m0, 0x8000
	s_nop 0
	global_load_lds_dwordx4 v[166:167], off
	s_nop 0
	s_nop 0
	s_nop 0
	s_nop 0
	ds_read_b128 a[16:19], v97
	ds_read_b128 a[20:23], v96
	ds_read_b128 a[24:27], v88 offset:49152
	ds_read_b128 a[28:31], v88 offset:53248
	s_waitcnt lgkmcnt(5)
	v_mfma_f32_32x32x16_bf16 v[48:63], a[0:3], a[8:11], v[48:63]
	v_mfma_f32_32x32x16_bf16 v[32:47], a[4:7], a[8:11], v[32:47]
	s_and_b32 m0, s32, 7
	s_lshl_b32 m0, m0, 11
	s_add_i32 m0, m0, 0x8400
	s_nop 0
	global_load_lds_dwordx4 v[168:169], off
	s_waitcnt lgkmcnt(4)
	v_mfma_f32_32x32x16_bf16 v[16:31], a[0:3], a[12:15], v[16:31]
	v_mfma_f32_32x32x16_bf16 v[0:15], a[4:7], a[12:15], v[0:15]
	s_nop 0
	s_nop 0
	s_nop 0
	s_nop 0
	s_waitcnt lgkmcnt(1)
	v_mfma_f32_32x32x16_bf16 v[48:63], a[16:19], a[24:27], v[48:63]
	v_mfma_f32_32x32x16_bf16 v[32:47], a[20:23], a[24:27], v[32:47]
	s_waitcnt vmcnt(6)
	s_waitcnt lgkmcnt(0)
	s_barrier
	ds_read_b128 a[12:15], v101
	ds_read_b128 a[8:11], v100
	ds_read_b128 a[4:7], v99
	ds_read_b128 a[0:3], v98
	v_mfma_f32_32x32x16_bf16 v[16:31], a[16:19], a[28:31], v[16:31]
	v_mfma_f32_32x32x16_bf16 v[0:15], a[20:23], a[28:31], v[0:15]
	s_nop 0
	s_nop 0
	s_nop 0
	s_nop 0
	ds_read_b128 a[16:19], v102
	ds_read_b128 a[20:23], v103
	ds_read_b128 a[24:27], v104
	ds_read_b128 a[28:31], v105
	s_waitcnt lgkmcnt(4)
	v_mfma_f32_32x32x16_bf16 v[48:63], a[0:3], a[8:11], v[48:63]
	v_mfma_f32_32x32x16_bf16 v[32:47], a[4:7], a[8:11], v[32:47]
	v_mfma_f32_32x32x16_bf16 v[16:31], a[0:3], a[12:15], v[16:31]
	v_mfma_f32_32x32x16_bf16 v[0:15], a[4:7], a[12:15], v[0:15]
	s_nop 0
	s_nop 0
	s_nop 0
	s_nop 0
	ds_read_b128 a[0:3], v106
	ds_read_b128 a[4:7], v107
	ds_read_b128 a[8:11], v108
	ds_read_b128 a[12:15], v109
	s_waitcnt lgkmcnt(5)
	v_mfma_f32_32x32x16_bf16 v[48:63], a[16:19], a[24:27], v[48:63]
	v_mfma_f32_32x32x16_bf16 v[32:47], a[20:23], a[24:27], v[32:47]
	s_waitcnt lgkmcnt(4)
	v_mfma_f32_32x32x16_bf16 v[16:31], a[16:19], a[28:31], v[16:31]
	v_mfma_f32_32x32x16_bf16 v[0:15], a[20:23], a[28:31], v[0:15]
	s_nop 0
	s_nop 0
	s_nop 0
	s_nop 0
	ds_read_b128 a[16:19], v110
	ds_read_b128 a[20:23], v111
	ds_read_b128 a[24:27], v112
	ds_read_b128 a[28:31], v113
	s_waitcnt lgkmcnt(5)
	v_mfma_f32_32x32x16_bf16 v[48:63], a[0:3], a[8:11], v[48:63]
	v_mfma_f32_32x32x16_bf16 v[32:47], a[4:7], a[8:11], v[32:47]
	s_waitcnt lgkmcnt(4)
	v_mfma_f32_32x32x16_bf16 v[16:31], a[0:3], a[12:15], v[16:31]
	v_mfma_f32_32x32x16_bf16 v[0:15], a[4:7], a[12:15], v[0:15]
	s_nop 0
	s_nop 0
	s_nop 0
	s_nop 0
	s_waitcnt lgkmcnt(1)
	v_mfma_f32_32x32x16_bf16 v[48:63], a[16:19], a[24:27], v[48:63]
	v_mfma_f32_32x32x16_bf16 v[32:47], a[20:23], a[24:27], v[32:47]
	s_waitcnt vmcnt(0)
	s_waitcnt lgkmcnt(0)
	s_barrier
	ds_read_b128 a[12:15], v82 offset:4096
	ds_read_b128 a[8:11], v82
	ds_read_b128 a[4:7], v83 offset:36864
	ds_read_b128 a[0:3], v83 offset:32768
	v_mfma_f32_32x32x16_bf16 v[16:31], a[16:19], a[28:31], v[16:31]
	v_mfma_f32_32x32x16_bf16 v[0:15], a[20:23], a[28:31], v[0:15]
	s_nop 0
	s_nop 0
	s_nop 0
	s_nop 0
	ds_read_b128 a[16:19], v85 offset:32768
	ds_read_b128 a[20:23], v85 offset:36864
	ds_read_b128 a[24:27], v84
	ds_read_b128 a[28:31], v84 offset:4096
	s_waitcnt lgkmcnt(4)
	v_mfma_f32_32x32x16_bf16 v[48:63], a[0:3], a[8:11], v[48:63]
	v_mfma_f32_32x32x16_bf16 v[32:47], a[4:7], a[8:11], v[32:47]
	v_mfma_f32_32x32x16_bf16 v[16:31], a[0:3], a[12:15], v[16:31]
	v_mfma_f32_32x32x16_bf16 v[0:15], a[4:7], a[12:15], v[0:15]
	s_nop 0
	s_nop 0
	s_nop 0
	s_nop 0
	ds_read_b128 a[0:3], v87 offset:32768
	ds_read_b128 a[4:7], v87 offset:36864
	ds_read_b128 a[8:11], v86
	ds_read_b128 a[12:15], v86 offset:4096
	s_waitcnt lgkmcnt(5)
	v_mfma_f32_32x32x16_bf16 v[48:63], a[16:19], a[24:27], v[48:63]
	v_mfma_f32_32x32x16_bf16 v[32:47], a[20:23], a[24:27], v[32:47]
	s_waitcnt lgkmcnt(4)
	v_mfma_f32_32x32x16_bf16 v[16:31], a[16:19], a[28:31], v[16:31]
	v_mfma_f32_32x32x16_bf16 v[0:15], a[20:23], a[28:31], v[0:15]
	s_nop 0
	s_nop 0
	s_nop 0
	s_waitcnt lgkmcnt(1)
	v_mfma_f32_32x32x16_bf16 v[48:63], a[0:3], a[8:11], v[48:63]
	v_mfma_f32_32x32x16_bf16 v[32:47], a[4:7], a[8:11], v[32:47]
	s_nop 0
	s_waitcnt lgkmcnt(0)
	v_mfma_f32_32x32x16_bf16 v[0:15], a[4:7], a[12:15], v[0:15]
	v_mfma_f32_32x32x16_bf16 v[16:31], a[0:3], a[12:15], v[16:31]
	ds_read_b128 v[66:69], v89 offset:32768
	ds_read_b128 v[70:73], v88
	ds_read_b128 v[74:77], v89 offset:36864
	ds_read_b128 v[82:85], v88 offset:4096
	s_waitcnt lgkmcnt(0)
	s_barrier
	s_waitcnt lgkmcnt(0)
	v_mfma_f32_32x32x16_bf16 v[48:63], v[66:69], v[70:73], v[48:63]
	v_mfma_f32_32x32x16_bf16 v[32:47], v[74:77], v[70:73], v[32:47]
	s_nop 10
	ds_write_b128 v64, v[48:51]
	ds_write_b128 v64, v[52:55] offset:32
	ds_write_b128 v64, v[56:59] offset:64
	ds_write_b128 v64, v[60:63] offset:96
	ds_write_b128 v64, v[32:35] offset:128
	v_mfma_f32_32x32x16_bf16 v[0:15], v[74:77], v[82:85], v[0:15]
	v_mfma_f32_32x32x16_bf16 v[16:31], v[66:69], v[82:85], v[16:31]
	s_setprio 0
	ds_write_b128 v64, v[36:39] offset:160
	ds_write_b128 v64, v[40:43] offset:192
	ds_write_b128 v64, v[44:47] offset:224
	s_nop 8
	ds_write_b128 v64, v[16:19] offset:16896
	ds_write_b128 v64, v[20:23] offset:16928
	ds_write_b128 v64, v[24:27] offset:16960
	ds_write_b128 v64, v[28:31] offset:16992
	ds_write_b128 v64, v[0:3] offset:17024
	ds_write_b128 v64, v[4:7] offset:17056
	ds_write_b128 v64, v[8:11] offset:17088
	ds_write_b128 v64, v[12:15] offset:17120
	s_waitcnt lgkmcnt(0)
	s_barrier
	v_lshl_or_b32 v0, v79, 2, s0
	v_ashrrev_i32_e32 v1, 31, v0
	v_lshl_add_u32 v4, v79, 4, 0
	v_cmp_eq_u32_e64 s[0:1], 0, v79
	v_lshl_add_u64 v[6:7], v[0:1], 2, s[92:93]
	v_lshl_add_u64 v[8:9], v[0:1], 1, s[20:21]
	s_branch .LBB0_96

.LBB0_159:
	v_mov_b32_e32 v78, v133
	s_lshl_b32 s22, s2, 8
	v_ashrrev_i32_e32 v6, 6, v78
	v_bfe_u32 v7, v78, 3, 3
	v_lshl_or_b32 v8, v6, 5, v7
	v_add_u32_e32 v0, s22, v8
	s_waitcnt lgkmcnt(0)
	v_ashrrev_i32_e32 v1, 31, v0
	v_lshlrev_b64 v[2:3], 11, v[0:1]
	v_bfe_u32 v1, v78, 4, 2
	v_readlane_b32 s0, v214, 4
	v_xor_b32_e32 v1, v1, v78
	v_readlane_b32 s1, v214, 5
	v_lshlrev_b32_e32 v1, 4, v1
	v_and_b32_e32 v64, 0x70, v1
	v_lshl_add_u64 v[2:3], s[0:1], 0, v[2:3]
	v_or_b32_e32 v1, 8, v8
	v_lshl_add_u64 v[66:67], v[2:3], 0, v[64:65]
	v_add_u32_e32 v2, s22, v1
	v_lshrrev_b32_e32 v1, 1, v1
	v_xor_b32_e32 v1, v1, v78
	v_ashrrev_i32_e32 v3, 31, v2
	v_lshlrev_b32_e32 v1, 4, v1
	v_or_b32_e32 v0, 16, v0
	v_lshlrev_b64 v[2:3], 11, v[2:3]
	v_and_b32_e32 v4, 0x70, v1
	v_ashrrev_i32_e32 v1, 31, v0
	v_lshl_add_u64 v[2:3], s[0:1], 0, v[2:3]
	v_mov_b32_e32 v5, v65
	v_lshlrev_b64 v[0:1], 11, v[0:1]
	v_lshl_add_u64 v[68:69], v[2:3], 0, v[4:5]
	v_lshl_add_u64 v[0:1], s[0:1], 0, v[0:1]
	v_or_b32_e32 v2, 24, v8
	v_lshl_add_u64 v[70:71], v[0:1], 0, v[64:65]
	v_add_u32_e32 v0, s22, v2
	v_lshrrev_b32_e32 v2, 1, v2
	v_ashrrev_i32_e32 v1, 31, v0
	v_xor_b32_e32 v2, v2, v78
	v_lshlrev_b64 v[0:1], 11, v[0:1]
	v_lshlrev_b32_e32 v2, 4, v2
	v_lshl_add_u64 v[0:1], s[0:1], 0, v[0:1]
	v_and_b32_e32 v2, 0x70, v2
	v_mov_b32_e32 v3, v65
	v_lshl_add_u64 v[72:73], v[0:1], 0, v[2:3]
	v_lshl_or_b32 v2, v6, 4, v7
	v_readlane_b32 s31, v214, 58
	v_lshlrev_b32_e32 v3, 12, v6
	v_add_u32_e32 v126, 0, v3
	v_add_u32_e32 v0, s31, v2
	v_ashrrev_i32_e32 v1, 31, v0
	v_lshlrev_b64 v[0:1], 11, v[0:1]
	s_waitcnt vmcnt(0)
	v_readfirstlane_b32 s37, v126
	v_add_u32_e32 v127, 0x400, v126
	v_lshl_add_u64 v[0:1], s[40:41], 0, v[0:1]
	v_or_b32_e32 v2, 8, v2
	s_waitcnt lgkmcnt(0)
	s_barrier
	s_mov_b32 m0, s37
	v_readfirstlane_b32 s38, v127
	v_add_u32_e32 v128, 0x800, v126
	v_lshlrev_b32_e32 v5, 11, v6
	v_and_b32_e32 v80, 1, v6
	v_lshl_add_u64 v[74:75], v[0:1], 0, v[64:65]
	v_add_u32_e32 v0, s31, v2
	v_lshrrev_b32_e32 v2, 1, v2
	global_load_lds_dwordx4 v[66:67], off
	s_mov_b32 m0, s38
	v_readfirstlane_b32 s39, v128
	v_add_u32_e32 v129, 0xc00, v126
	v_add_u32_e32 v6, 0, v5
	v_ashrrev_i32_e32 v1, 31, v0
	v_xor_b32_e32 v2, v2, v78
	global_load_lds_dwordx4 v[68:69], off
	s_mov_b32 m0, s39
	v_readfirstlane_b32 s48, v129
	v_add_u32_e32 v131, 0x8000, v6
	v_lshlrev_b64 v[0:1], 11, v[0:1]
	v_lshlrev_b32_e32 v2, 4, v2
	global_load_lds_dwordx4 v[70:71], off
	s_mov_b32 m0, s48
	v_readfirstlane_b32 s49, v131
	v_add_u32_e32 v130, 0x8400, v6
	v_lshl_add_u64 v[0:1], s[40:41], 0, v[0:1]
	v_and_b32_e32 v64, 0x70, v2
	global_load_lds_dwordx4 v[72:73], off
	s_mov_b32 m0, s49
	v_readfirstlane_b32 s53, v130
	v_add_u32_e32 v120, 0xc000, v126
	v_lshl_add_u64 v[76:77], v[0:1], 0, v[64:65]
	global_load_lds_dwordx4 v[74:75], off
	s_mov_b32 m0, s53
	s_mov_b64 s[0:1], 0x80
	v_readfirstlane_b32 s28, v120
	v_add_u32_e32 v121, 0xc400, v126
	global_load_lds_dwordx4 v[76:77], off
	v_lshl_add_u64 v[0:1], v[66:67], 0, s[0:1]
	s_mov_b32 m0, s28
	v_readfirstlane_b32 s29, v121
	v_add_u32_e32 v122, 0xc800, v126
	global_load_lds_dwordx4 v[0:1], off
	v_lshl_add_u64 v[0:1], v[68:69], 0, s[0:1]
	s_mov_b32 m0, s29
	v_readfirstlane_b32 s33, v122
	v_add_u32_e32 v123, 0xcc00, v126
	global_load_lds_dwordx4 v[0:1], off
	v_lshl_add_u64 v[0:1], v[70:71], 0, s[0:1]
	s_mov_b32 m0, s33
	v_readfirstlane_b32 s34, v123
	v_add_u32_e32 v124, s85, v5
	global_load_lds_dwordx4 v[0:1], off
	v_lshl_add_u64 v[0:1], v[72:73], 0, s[0:1]
	s_mov_b32 m0, s34
	v_readfirstlane_b32 s35, v124
	v_add_u32_e32 v125, 0x14400, v6
	global_load_lds_dwordx4 v[0:1], off
	v_lshl_add_u64 v[0:1], v[74:75], 0, s[0:1]
	s_mov_b32 m0, s35
	v_readfirstlane_b32 s36, v125
	global_load_lds_dwordx4 v[0:1], off
	v_lshl_add_u64 v[0:1], v[76:77], 0, s[0:1]
	s_mov_b32 m0, s36
	v_lshrrev_b32_e32 v2, 1, v78
	v_bfe_u32 v64, v78, 5, 1
	global_load_lds_dwordx4 v[0:1], off
	v_add_u32_e32 v114, s3, v3
	v_bitop3_b32 v0, v2, v64, 7 bitop3:0x6c
	s_waitcnt vmcnt(6)
	s_mov_b64 s[46:47], 0x100
	v_readfirstlane_b32 s0, v114
	v_add_u32_e32 v115, 0x400, v114
	v_lshlrev_b32_e32 v132, 4, v0
	s_waitcnt lgkmcnt(0)
	s_barrier
	v_lshl_add_u64 v[0:1], v[66:67], 0, s[46:47]
	s_mov_b32 m0, s0
	v_readfirstlane_b32 s1, v115
	v_add_u32_e32 v116, 0x800, v114
	global_load_lds_dwordx4 v[0:1], off
	v_lshl_add_u64 v[0:1], v[68:69], 0, s[46:47]
	s_mov_b32 m0, s1
	v_readfirstlane_b32 s20, v116
	v_add_u32_e32 v117, 0xc00, v114
	v_readlane_b32 s23, v212, 31
	v_and_b32_e32 v79, 31, v78
	global_load_lds_dwordx4 v[0:1], off
	v_lshl_add_u64 v[0:1], v[70:71], 0, s[46:47]
	s_mov_b32 m0, s20
	v_readfirstlane_b32 s21, v117
	v_add_u32_e32 v118, s23, v5
	v_add_u32_e32 v2, s3, v5
	v_lshlrev_b32_e32 v4, 7, v79
	global_load_lds_dwordx4 v[0:1], off
	v_lshl_add_u64 v[0:1], v[72:73], 0, s[46:47]
	s_mov_b32 m0, s21
	v_readfirstlane_b32 s23, v118
	v_add_u32_e32 v119, 0x8400, v2
	v_lshl_or_b32 v102, v80, 13, v4
	global_load_lds_dwordx4 v[0:1], off
	v_lshl_add_u64 v[0:1], v[74:75], 0, s[46:47]
	s_mov_b32 m0, s23
	v_readfirstlane_b32 s24, v119
	global_load_lds_dwordx4 v[0:1], off
	v_lshl_add_u64 v[0:1], v[76:77], 0, s[46:47]
	s_mov_b32 m0, s24
	v_add_u32_e32 v100, 0, v102
	global_load_lds_dwordx4 v[0:1], off
	v_add_u32_e32 v83, v100, v132
	v_ashrrev_i32_e32 v81, 7, v78
	ds_read_b128 a[0:3], v83 offset:32768
	ds_read_b128 a[4:7], v83 offset:36864
	v_lshl_or_b32 v134, v81, 13, v4
	v_add_u32_e32 v101, 0, v134
	v_add_u32_e32 v82, v101, v132
	ds_read_b128 a[8:11], v82
	ds_read_b128 a[12:15], v82 offset:4096
	v_lshrrev_b32_e32 v182, 6, v133
	s_nop 0
	v_readfirstlane_b32 s32, v182
	s_cmp_ge_u32 s32, 4
	s_cbranch_scc0 .Lmy_prio1
	s_setprio 1
.Lmy_prio1:
	s_waitcnt lgkmcnt(1)
	v_mfma_f32_32x32x16_bf16 v[48:63], a[0:3], a[8:11], 0
	v_bfe_u32 v103, v78, 1, 3
	s_mov_b64 s[46:47], 0x180
	s_nop 0
	s_add_i32 s30, 0, 0xc000
	v_or_b32_e32 v143, 0x8000, v102
	v_or_b32_e32 v144, 0x9000, v102
	v_add_u32_e32 v145, s3, v134
	s_waitcnt vmcnt(12)
	v_mfma_f32_32x32x16_bf16 v[32:47], a[4:7], a[8:11], 0
	v_lshl_or_b32 v81, v81, 6, v79
	v_mul_lo_u32 v81, v81, s26
	s_mov_b64 s[80:81], 0x200
	s_waitcnt lgkmcnt(0)
	v_mfma_f32_32x32x16_bf16 v[16:31], a[0:3], a[12:15], 0
	v_bitop3_b32 v0, v64, v103, 2 bitop3:0x36
	v_lshlrev_b32_e32 v138, 4, v0
	v_add_u32_e32 v84, v101, v138
	ds_read_b128 a[28:31], v84 offset:4096
	s_nop 0
	s_nop 0
	ds_read_b128 a[24:27], v84
	s_nop 0
	v_add_u32_e32 v85, v100, v138
	ds_read_b128 a[20:23], v85 offset:36864
	s_nop 0
	s_nop 0
	ds_read_b128 a[16:19], v85 offset:32768
	s_nop 0
	s_nop 0
	s_nop 0
	s_nop 0
	s_nop 0
	s_nop 0
	v_mfma_f32_32x32x16_bf16 v[0:15], a[4:7], a[12:15], 0
	s_nop 0
	s_waitcnt lgkmcnt(0)
	v_mfma_f32_32x32x16_bf16 v[48:63], a[16:19], a[24:27], v[48:63]
	v_mfma_f32_32x32x16_bf16 v[32:47], a[20:23], a[24:27], v[32:47]
	v_mfma_f32_32x32x16_bf16 v[16:31], a[16:19], a[28:31], v[16:31]
	v_bitop3_b32 v86, v64, v103, 4 bitop3:0x36
	v_lshlrev_b32_e32 v139, 4, v86
	v_add_u32_e32 v86, v101, v139
	ds_read_b128 a[12:15], v86 offset:4096
	s_nop 0
	s_nop 0
	ds_read_b128 a[8:11], v86
	s_nop 0
	v_add_u32_e32 v87, v100, v139
	ds_read_b128 a[4:7], v87 offset:36864
	s_nop 0
	s_nop 0
	ds_read_b128 a[0:3], v87 offset:32768
	s_nop 0
	s_nop 0
	s_nop 0
	v_mfma_f32_32x32x16_bf16 v[0:15], a[20:23], a[28:31], v[0:15]
	s_nop 0
	s_nop 0
	s_nop 0
	s_nop 0
	s_waitcnt lgkmcnt(0)
	v_mfma_f32_32x32x16_bf16 v[48:63], a[0:3], a[8:11], v[48:63]
	v_mfma_f32_32x32x16_bf16 v[32:47], a[4:7], a[8:11], v[32:47]
	v_mfma_f32_32x32x16_bf16 v[16:31], a[0:3], a[12:15], v[16:31]
	v_bitop3_b32 v88, v64, v103, 6 bitop3:0x36
	v_lshlrev_b32_e32 v142, 4, v88
	v_add_u32_e32 v88, v101, v142
	ds_read_b128 a[28:31], v88 offset:4096
	s_nop 0
	s_nop 0
	ds_read_b128 a[24:27], v88
	s_nop 0
	v_add_u32_e32 v89, v100, v142
	ds_read_b128 a[20:23], v89 offset:36864
	s_nop 0
	s_nop 0
	ds_read_b128 a[16:19], v89 offset:32768
	s_nop 0
	s_nop 0
	s_nop 0
	v_lshlrev_b32_e32 v64, 4, v64
	v_lshl_or_b32 v64, v80, 8, v64
	v_add3_u32 v64, 0, v81, v64
	v_mfma_f32_32x32x16_bf16 v[0:15], a[4:7], a[12:15], v[0:15]
	s_nop 0
	s_nop 0
	s_nop 0
	s_nop 0
	s_waitcnt lgkmcnt(0)
	v_mfma_f32_32x32x16_bf16 v[48:63], a[16:19], a[24:27], v[48:63]
	v_mfma_f32_32x32x16_bf16 v[32:47], a[20:23], a[24:27], v[32:47]
	s_waitcnt vmcnt(6)
	s_waitcnt lgkmcnt(0)
	s_barrier
	ds_read_b128 a[12:15], v82 offset:53248
	ds_read_b128 a[8:11], v82 offset:49152
	v_add_u32_e32 v90, s30, v132
	v_add_u32_e32 v92, v90, v143
	v_add_u32_e32 v90, v90, v144
	ds_read_b128 a[4:7], v90
	ds_read_b128 a[0:3], v92
	v_mfma_f32_32x32x16_bf16 v[16:31], a[16:19], a[28:31], v[16:31]
	v_lshl_add_u64 v[158:159], v[66:67], 0, s[46:47]
	s_nop 0
	v_lshl_add_u64 v[160:161], v[68:69], 0, s[46:47]
	s_nop 0
	s_nop 0
	s_nop 0
	v_lshl_add_u64 v[162:163], v[70:71], 0, s[46:47]
	s_nop 0
	v_mfma_f32_32x32x16_bf16 v[0:15], a[20:23], a[28:31], v[0:15]
	s_and_b32 m0, s32, 7
	s_lshl_b32 m0, m0, 12
	s_add_i32 m0, m0, 0x0
	s_nop 0
	global_load_lds_dwordx4 v[158:159], off
	s_nop 0
	v_lshl_add_u64 v[164:165], v[72:73], 0, s[46:47]
	s_nop 0
	s_nop 0
	s_nop 0
	v_lshl_add_u64 v[166:167], v[74:75], 0, s[46:47]
	s_nop 0
	s_nop 0
	s_nop 0
	v_lshl_add_u64 v[168:169], v[76:77], 0, s[46:47]
	s_nop 0
	s_mov_b64 s[46:47], 0x200
	s_nop 0
	s_nop 0
	s_nop 0
	s_nop 0
	s_nop 0
	s_nop 0
	s_nop 0
	s_nop 0
	v_add_u32_e32 v91, s30, v138
	v_add_u32_e32 v93, v91, v143
	ds_read_b128 a[16:19], v93
	v_add_u32_e32 v91, v91, v144
	ds_read_b128 a[20:23], v91
	ds_read_b128 a[24:27], v84 offset:49152
	ds_read_b128 a[28:31], v84 offset:53248
	s_waitcnt lgkmcnt(4)
	v_mfma_f32_32x32x16_bf16 v[48:63], a[0:3], a[8:11], v[48:63]
	s_nop 0
	s_nop 0
	s_nop 0
	s_nop 0
	v_mfma_f32_32x32x16_bf16 v[32:47], a[4:7], a[8:11], v[32:47]
	s_and_b32 m0, s32, 7
	s_lshl_b32 m0, m0, 12
	s_add_i32 m0, m0, 0x400
	s_nop 0
	global_load_lds_dwordx4 v[160:161], off
	v_mfma_f32_32x32x16_bf16 v[16:31], a[0:3], a[12:15], v[16:31]
	v_mfma_f32_32x32x16_bf16 v[0:15], a[4:7], a[12:15], v[0:15]
	s_and_b32 m0, s32, 7
	s_lshl_b32 m0, m0, 12
	s_add_i32 m0, m0, 0x800
	s_nop 0
	global_load_lds_dwordx4 v[162:163], off
	s_nop 0
	s_nop 0
	s_nop 0
	s_nop 0
	v_add_u32_e32 v94, s30, v139
	v_add_u32_e32 v95, v94, v143
	ds_read_b128 a[0:3], v95
	v_add_u32_e32 v94, v94, v144
	ds_read_b128 a[4:7], v94
	ds_read_b128 a[8:11], v86 offset:49152
	ds_read_b128 a[12:15], v86 offset:53248
	s_waitcnt lgkmcnt(5)
	v_mfma_f32_32x32x16_bf16 v[48:63], a[16:19], a[24:27], v[48:63]
	v_mfma_f32_32x32x16_bf16 v[32:47], a[20:23], a[24:27], v[32:47]
	s_and_b32 m0, s32, 7
	s_lshl_b32 m0, m0, 12
	s_add_i32 m0, m0, 0xc00
	s_nop 0
	global_load_lds_dwordx4 v[164:165], off
	s_waitcnt lgkmcnt(4)
	v_mfma_f32_32x32x16_bf16 v[16:31], a[16:19], a[28:31], v[16:31]
	s_nop 0
	s_nop 0
	s_nop 0
	v_mfma_f32_32x32x16_bf16 v[0:15], a[20:23], a[28:31], v[0:15]
	s_and_b32 m0, s32, 7
	s_lshl_b32 m0, m0, 11
	s_add_i32 m0, m0, 0x8000
	s_nop 0
	global_load_lds_dwordx4 v[166:167], off
	s_nop 0
	s_nop 0
	s_nop 0
	s_nop 0
	v_add_u32_e32 v96, s30, v142
	v_add_u32_e32 v97, v96, v143
	ds_read_b128 a[16:19], v97
	v_add_u32_e32 v96, v96, v144
	ds_read_b128 a[20:23], v96
	ds_read_b128 a[24:27], v88 offset:49152
	ds_read_b128 a[28:31], v88 offset:53248
	s_waitcnt lgkmcnt(5)
	v_mfma_f32_32x32x16_bf16 v[48:63], a[0:3], a[8:11], v[48:63]
	v_mfma_f32_32x32x16_bf16 v[32:47], a[4:7], a[8:11], v[32:47]
	s_and_b32 m0, s32, 7
	s_lshl_b32 m0, m0, 11
	s_add_i32 m0, m0, 0x8400
	s_nop 0
	global_load_lds_dwordx4 v[168:169], off
	s_waitcnt lgkmcnt(4)
	v_mfma_f32_32x32x16_bf16 v[16:31], a[0:3], a[12:15], v[16:31]
	s_nop 0
	s_nop 0
	s_nop 0
	v_mfma_f32_32x32x16_bf16 v[0:15], a[4:7], a[12:15], v[0:15]
	s_nop 0
	s_nop 0
	s_nop 0
	s_nop 0
	s_waitcnt lgkmcnt(1)
	v_mfma_f32_32x32x16_bf16 v[48:63], a[16:19], a[24:27], v[48:63]
	v_mfma_f32_32x32x16_bf16 v[32:47], a[20:23], a[24:27], v[32:47]
	s_waitcnt vmcnt(6)
	s_waitcnt lgkmcnt(0)
	s_barrier
	v_add_u32_e32 v100, v145, v132
	ds_read_b128 a[8:11], v100
	v_add_u32_e32 v101, s3, v132
	v_add_u32_e32 v99, v101, v144
	ds_read_b128 a[4:7], v99
	s_nop 0
	v_add_u32_e32 v98, v101, v143
	v_or_b32_e32 v132, 0x1000, v134
	v_add_u32_e32 v101, v101, v132
	ds_read_b128 a[12:15], v101
	ds_read_b128 a[0:3], v98
	v_mfma_f32_32x32x16_bf16 v[16:31], a[16:19], a[28:31], v[16:31]
	v_lshl_add_u64 v[170:171], v[66:67], 0, s[46:47]
	s_nop 0
	v_lshl_add_u64 v[172:173], v[68:69], 0, s[46:47]
	s_nop 0
	s_nop 0
	s_nop 0
	v_lshl_add_u64 v[174:175], v[70:71], 0, s[46:47]
	s_nop 0
	v_mfma_f32_32x32x16_bf16 v[0:15], a[20:23], a[28:31], v[0:15]
	s_and_b32 m0, s32, 7
	s_lshl_b32 m0, m0, 12
	s_add_i32 m0, m0, 0xc000
	s_nop 0
	global_load_lds_dwordx4 v[170:171], off
	s_nop 0
	v_lshl_add_u64 v[176:177], v[72:73], 0, s[46:47]
	s_nop 0
	s_nop 0
	s_nop 0
	v_lshl_add_u64 v[178:179], v[74:75], 0, s[46:47]
	s_nop 0
	s_nop 0
	s_nop 0
	v_lshl_add_u64 v[180:181], v[76:77], 0, s[46:47]
	s_nop 0
	s_mov_b64 s[46:47], 0x280
	s_nop 0
	s_nop 0
	s_nop 0
	s_nop 0
	s_nop 0
	s_nop 0
	s_nop 0
	s_nop 0
	v_add_u32_e32 v105, s3, v138
	v_add_u32_e32 v102, v105, v143
	ds_read_b128 a[16:19], v102
	v_add_u32_e32 v103, v105, v144
	ds_read_b128 a[20:23], v103
	v_add_u32_e32 v104, v145, v138
	ds_read_b128 a[24:27], v104
	v_add_u32_e32 v105, v105, v132
	ds_read_b128 a[28:31], v105
	s_waitcnt lgkmcnt(4)
	v_mfma_f32_32x32x16_bf16 v[48:63], a[0:3], a[8:11], v[48:63]
	s_nop 0
	v_mfma_f32_32x32x16_bf16 v[32:47], a[4:7], a[8:11], v[32:47]
	s_and_b32 m0, s32, 7
	s_lshl_b32 m0, m0, 12
	s_add_i32 m0, m0, 0xc400
	s_nop 0
	global_load_lds_dwordx4 v[172:173], off
	s_nop 0
	s_nop 0
	s_nop 0
	s_nop 0
	s_nop 0
	v_mfma_f32_32x32x16_bf16 v[16:31], a[0:3], a[12:15], v[16:31]
	s_nop 0
	v_mfma_f32_32x32x16_bf16 v[0:15], a[4:7], a[12:15], v[0:15]
	s_and_b32 m0, s32, 7
	s_lshl_b32 m0, m0, 12
	s_add_i32 m0, m0, 0xc800
	s_nop 0
	global_load_lds_dwordx4 v[174:175], off
	s_nop 0
	s_nop 0
	s_nop 0
	v_add_u32_e32 v109, s3, v139
	v_add_u32_e32 v106, v109, v143
	ds_read_b128 a[0:3], v106
	v_add_u32_e32 v107, v109, v144
	ds_read_b128 a[4:7], v107
	v_add_u32_e32 v108, v145, v139
	ds_read_b128 a[8:11], v108
	v_add_u32_e32 v109, v109, v132
	ds_read_b128 a[12:15], v109
	s_waitcnt lgkmcnt(5)
	v_mfma_f32_32x32x16_bf16 v[48:63], a[16:19], a[24:27], v[48:63]
	v_mfma_f32_32x32x16_bf16 v[32:47], a[20:23], a[24:27], v[32:47]
	s_and_b32 m0, s32, 7
	s_lshl_b32 m0, m0, 12
	s_add_i32 m0, m0, 0xcc00
	s_nop 0
	global_load_lds_dwordx4 v[176:177], off
	s_waitcnt lgkmcnt(4)
	v_mfma_f32_32x32x16_bf16 v[16:31], a[16:19], a[28:31], v[16:31]
	s_nop 0
	s_nop 0
	s_nop 0
	s_nop 0
	s_nop 0
	s_nop 0
	v_mfma_f32_32x32x16_bf16 v[0:15], a[20:23], a[28:31], v[0:15]
	s_and_b32 m0, s32, 7
	s_lshl_b32 m0, m0, 11
	s_add_i32 m0, m0, 0x14000
	s_nop 0
	global_load_lds_dwordx4 v[178:179], off
	s_nop 0
	s_nop 0
	s_nop 0
	v_add_u32_e32 v113, s3, v142
	v_add_u32_e32 v110, v113, v143
	ds_read_b128 a[16:19], v110
	v_add_u32_e32 v111, v113, v144
	ds_read_b128 a[20:23], v111
	v_add_u32_e32 v112, v145, v142
	ds_read_b128 a[24:27], v112
	v_add_u32_e32 v113, v113, v132
	ds_read_b128 a[28:31], v113
	s_waitcnt lgkmcnt(5)
	v_mfma_f32_32x32x16_bf16 v[48:63], a[0:3], a[8:11], v[48:63]
	v_mfma_f32_32x32x16_bf16 v[32:47], a[4:7], a[8:11], v[32:47]
	s_and_b32 m0, s32, 7
	s_lshl_b32 m0, m0, 11
	s_add_i32 m0, m0, 0x14400
	s_nop 0
	global_load_lds_dwordx4 v[180:181], off
	s_waitcnt lgkmcnt(4)
	v_mfma_f32_32x32x16_bf16 v[16:31], a[0:3], a[12:15], v[16:31]
	s_nop 0
	s_nop 0
	s_nop 0
	s_nop 0
	s_nop 0
	s_nop 0
	v_mfma_f32_32x32x16_bf16 v[0:15], a[4:7], a[12:15], v[0:15]
	s_nop 0
	s_nop 0
	s_nop 0
	s_waitcnt lgkmcnt(1)
	v_mfma_f32_32x32x16_bf16 v[48:63], a[16:19], a[24:27], v[48:63]
	v_mfma_f32_32x32x16_bf16 v[32:47], a[20:23], a[24:27], v[32:47]
	s_waitcnt vmcnt(6)
	s_waitcnt lgkmcnt(0)
	s_barrier
	ds_read_b128 a[12:15], v82 offset:4096
	ds_read_b128 a[8:11], v82
	ds_read_b128 a[4:7], v83 offset:36864
	ds_read_b128 a[0:3], v83 offset:32768
	v_mfma_f32_32x32x16_bf16 v[16:31], a[16:19], a[28:31], v[16:31]
	v_lshl_add_u64 v[158:159], v[66:67], 0, s[46:47]
	s_nop 0
	v_lshl_add_u64 v[160:161], v[68:69], 0, s[46:47]
	s_nop 0
	s_nop 0
	s_nop 0
	v_lshl_add_u64 v[162:163], v[70:71], 0, s[46:47]
	s_nop 0
	v_mfma_f32_32x32x16_bf16 v[0:15], a[20:23], a[28:31], v[0:15]
	s_and_b32 m0, s32, 7
	s_lshl_b32 m0, m0, 12
	s_add_i32 m0, m0, 0x18000
	s_nop 0
	global_load_lds_dwordx4 v[158:159], off
	s_nop 0
	v_lshl_add_u64 v[164:165], v[72:73], 0, s[46:47]
	s_nop 0
	s_nop 0
	s_nop 0
	v_lshl_add_u64 v[166:167], v[74:75], 0, s[46:47]
	s_nop 0
	s_nop 0
	s_nop 0
	v_lshl_add_u64 v[168:169], v[76:77], 0, s[46:47]
	s_nop 0
	s_mov_b64 s[46:47], 0x300
	s_nop 0
	s_nop 0
	s_nop 0
	s_nop 0
	s_nop 0
	ds_read_b128 a[16:19], v85 offset:32768
	ds_read_b128 a[20:23], v85 offset:36864
	ds_read_b128 a[24:27], v84
	ds_read_b128 a[28:31], v84 offset:4096
	s_waitcnt lgkmcnt(4)
	v_mfma_f32_32x32x16_bf16 v[48:63], a[0:3], a[8:11], v[48:63]
	s_nop 0
	v_mfma_f32_32x32x16_bf16 v[32:47], a[4:7], a[8:11], v[32:47]
	s_and_b32 m0, s32, 7
	s_lshl_b32 m0, m0, 12
	s_add_i32 m0, m0, 0x18400
	s_nop 0
	global_load_lds_dwordx4 v[160:161], off
	v_mfma_f32_32x32x16_bf16 v[16:31], a[0:3], a[12:15], v[16:31]
	v_mfma_f32_32x32x16_bf16 v[0:15], a[4:7], a[12:15], v[0:15]
	s_and_b32 m0, s32, 7
	s_lshl_b32 m0, m0, 12
	s_add_i32 m0, m0, 0x18800
	s_nop 0
	global_load_lds_dwordx4 v[162:163], off
	s_nop 0
	s_nop 0
	s_nop 0
	s_nop 0
	ds_read_b128 a[0:3], v87 offset:32768
	ds_read_b128 a[4:7], v87 offset:36864
	ds_read_b128 a[8:11], v86
	ds_read_b128 a[12:15], v86 offset:4096
	s_waitcnt lgkmcnt(5)
	v_mfma_f32_32x32x16_bf16 v[48:63], a[16:19], a[24:27], v[48:63]
	v_mfma_f32_32x32x16_bf16 v[32:47], a[20:23], a[24:27], v[32:47]
	s_and_b32 m0, s32, 7
	s_lshl_b32 m0, m0, 12
	s_add_i32 m0, m0, 0x18c00
	s_nop 0
	global_load_lds_dwordx4 v[164:165], off
	s_waitcnt lgkmcnt(4)
	v_mfma_f32_32x32x16_bf16 v[16:31], a[16:19], a[28:31], v[16:31]
	v_mfma_f32_32x32x16_bf16 v[0:15], a[20:23], a[28:31], v[0:15]
	s_and_b32 m0, s32, 7
	s_lshl_b32 m0, m0, 11
	s_add_i32 m0, m0, 0x20000
	s_nop 0
	global_load_lds_dwordx4 v[166:167], off
	s_nop 0
	s_nop 0
	s_nop 0
	s_nop 0
	ds_read_b128 a[16:19], v89 offset:32768
	ds_read_b128 a[20:23], v89 offset:36864
	ds_read_b128 a[24:27], v88
	ds_read_b128 a[28:31], v88 offset:4096
	s_waitcnt lgkmcnt(5)
	v_mfma_f32_32x32x16_bf16 v[48:63], a[0:3], a[8:11], v[48:63]
	v_mfma_f32_32x32x16_bf16 v[32:47], a[4:7], a[8:11], v[32:47]
	s_and_b32 m0, s32, 7
	s_lshl_b32 m0, m0, 11
	s_add_i32 m0, m0, 0x20400
	s_nop 0
	global_load_lds_dwordx4 v[168:169], off
	s_waitcnt lgkmcnt(4)
	v_mfma_f32_32x32x16_bf16 v[16:31], a[0:3], a[12:15], v[16:31]
	v_mfma_f32_32x32x16_bf16 v[0:15], a[4:7], a[12:15], v[0:15]
	s_nop 0
	s_nop 0
	s_nop 0
	s_nop 0
	s_waitcnt lgkmcnt(1)
	v_mfma_f32_32x32x16_bf16 v[48:63], a[16:19], a[24:27], v[48:63]
	v_mfma_f32_32x32x16_bf16 v[32:47], a[20:23], a[24:27], v[32:47]
	s_waitcnt vmcnt(6)
	s_waitcnt lgkmcnt(0)
	s_barrier
	ds_read_b128 a[12:15], v82 offset:53248
	ds_read_b128 a[8:11], v82 offset:49152
	ds_read_b128 a[4:7], v90
	ds_read_b128 a[0:3], v92
	v_mfma_f32_32x32x16_bf16 v[16:31], a[16:19], a[28:31], v[16:31]
	v_lshl_add_u64 v[170:171], v[66:67], 0, s[46:47]
	s_nop 0
	v_lshl_add_u64 v[172:173], v[68:69], 0, s[46:47]
	s_nop 0
	s_nop 0
	s_nop 0
	v_lshl_add_u64 v[174:175], v[70:71], 0, s[46:47]
	s_nop 0
	v_mfma_f32_32x32x16_bf16 v[0:15], a[20:23], a[28:31], v[0:15]
	s_and_b32 m0, s32, 7
	s_lshl_b32 m0, m0, 12
	s_add_i32 m0, m0, 0x0
	s_nop 0
	global_load_lds_dwordx4 v[170:171], off
	s_nop 0
	v_lshl_add_u64 v[176:177], v[72:73], 0, s[46:47]
	s_nop 0
	s_mov_b64 s[38:39], 0x380
	s_nop 0
	v_lshl_add_u64 v[178:179], v[74:75], 0, s[46:47]
	s_nop 0
	v_readfirstlane_b32 s48, v117
	s_nop 0
	v_lshl_add_u64 v[180:181], v[76:77], 0, s[46:47]
	s_nop 0
	s_mov_b64 s[46:47], 0x580
	s_nop 0
	s_nop 0
	s_nop 0
	s_nop 0
	s_nop 0
	ds_read_b128 a[16:19], v93
	ds_read_b128 a[20:23], v91
	ds_read_b128 a[24:27], v84 offset:49152
	ds_read_b128 a[28:31], v84 offset:53248
	s_waitcnt lgkmcnt(4)
	v_mfma_f32_32x32x16_bf16 v[48:63], a[0:3], a[8:11], v[48:63]
	s_nop 0
	v_readfirstlane_b32 s49, v118
	v_readfirstlane_b32 s53, v119
	v_mfma_f32_32x32x16_bf16 v[32:47], a[4:7], a[8:11], v[32:47]
	s_and_b32 m0, s32, 7
	s_lshl_b32 m0, m0, 12
	s_add_i32 m0, m0, 0x400
	s_nop 0
	global_load_lds_dwordx4 v[172:173], off
	v_mfma_f32_32x32x16_bf16 v[16:31], a[0:3], a[12:15], v[16:31]
	v_mfma_f32_32x32x16_bf16 v[0:15], a[4:7], a[12:15], v[0:15]
	s_and_b32 m0, s32, 7
	s_lshl_b32 m0, m0, 12
	s_add_i32 m0, m0, 0x800
	s_nop 0
	global_load_lds_dwordx4 v[174:175], off
	s_nop 0
	s_nop 0
	s_nop 0
	s_nop 0
	ds_read_b128 a[0:3], v95
	ds_read_b128 a[4:7], v94
	ds_read_b128 a[8:11], v86 offset:49152
	ds_read_b128 a[12:15], v86 offset:53248
	s_waitcnt lgkmcnt(5)
	v_mfma_f32_32x32x16_bf16 v[48:63], a[16:19], a[24:27], v[48:63]
	v_mfma_f32_32x32x16_bf16 v[32:47], a[20:23], a[24:27], v[32:47]
	s_and_b32 m0, s32, 7
	s_lshl_b32 m0, m0, 12
	s_add_i32 m0, m0, 0xc00
	s_nop 0
	global_load_lds_dwordx4 v[176:177], off
	s_waitcnt lgkmcnt(4)
	v_mfma_f32_32x32x16_bf16 v[16:31], a[16:19], a[28:31], v[16:31]
	v_mfma_f32_32x32x16_bf16 v[0:15], a[20:23], a[28:31], v[0:15]
	s_and_b32 m0, s32, 7
	s_lshl_b32 m0, m0, 11
	s_add_i32 m0, m0, 0x8000
	s_nop 0
	global_load_lds_dwordx4 v[178:179], off
	s_nop 0
	s_nop 0
	s_nop 0
	s_nop 0
	ds_read_b128 a[16:19], v97
	ds_read_b128 a[20:23], v96
	ds_read_b128 a[24:27], v88 offset:49152
	ds_read_b128 a[28:31], v88 offset:53248
	s_waitcnt lgkmcnt(5)
	v_mfma_f32_32x32x16_bf16 v[48:63], a[0:3], a[8:11], v[48:63]
	v_mfma_f32_32x32x16_bf16 v[32:47], a[4:7], a[8:11], v[32:47]
	s_and_b32 m0, s32, 7
	s_lshl_b32 m0, m0, 11
	s_add_i32 m0, m0, 0x8400
	s_nop 0
	global_load_lds_dwordx4 v[180:181], off
	s_waitcnt lgkmcnt(4)
	v_mfma_f32_32x32x16_bf16 v[16:31], a[0:3], a[12:15], v[16:31]
	v_mfma_f32_32x32x16_bf16 v[0:15], a[4:7], a[12:15], v[0:15]
	s_nop 0
	s_nop 0
	s_nop 0
	s_nop 0
	s_waitcnt lgkmcnt(1)
	v_mfma_f32_32x32x16_bf16 v[48:63], a[16:19], a[24:27], v[48:63]
	v_mfma_f32_32x32x16_bf16 v[32:47], a[20:23], a[24:27], v[32:47]
	s_waitcnt vmcnt(6)
	s_waitcnt lgkmcnt(0)
	s_barrier
	ds_read_b128 a[12:15], v101
	ds_read_b128 a[8:11], v100
	ds_read_b128 a[4:7], v99
	ds_read_b128 a[0:3], v98
	v_mfma_f32_32x32x16_bf16 v[16:31], a[16:19], a[28:31], v[16:31]
	v_lshl_add_u64 v[158:159], v[66:67], 0, s[38:39]
	s_nop 0
	v_lshl_add_u64 v[160:161], v[68:69], 0, s[38:39]
	s_nop 0
	s_mov_b64 s[28:29], 0x400
	s_nop 0
	v_lshl_add_u64 v[162:163], v[70:71], 0, s[38:39]
	s_nop 0
	v_mfma_f32_32x32x16_bf16 v[0:15], a[20:23], a[28:31], v[0:15]
	s_and_b32 m0, s32, 7
	s_lshl_b32 m0, m0, 12
	s_add_i32 m0, m0, 0xc000
	s_nop 0
	global_load_lds_dwordx4 v[158:159], off
	s_nop 0
	v_lshl_add_u64 v[164:165], v[72:73], 0, s[38:39]
	s_nop 0
	v_readfirstlane_b32 s33, v122
	s_nop 0
	v_lshl_add_u64 v[166:167], v[74:75], 0, s[38:39]
	s_nop 0
	v_readfirstlane_b32 s34, v123
	s_nop 0
	v_lshl_add_u64 v[168:169], v[76:77], 0, s[38:39]
	s_nop 0
	s_mov_b64 s[36:37], 0x500
	s_nop 0
	s_nop 0
	s_nop 0
	s_nop 0
	s_nop 0
	ds_read_b128 a[16:19], v102
	ds_read_b128 a[20:23], v103
	ds_read_b128 a[24:27], v104
	ds_read_b128 a[28:31], v105
	s_waitcnt lgkmcnt(4)
	v_mfma_f32_32x32x16_bf16 v[48:63], a[0:3], a[8:11], v[48:63]
	s_nop 0
	v_readfirstlane_b32 s0, v126
	v_readfirstlane_b32 s35, v124
	v_readfirstlane_b32 s38, v115
	v_readfirstlane_b32 s39, v116
	v_mfma_f32_32x32x16_bf16 v[32:47], a[4:7], a[8:11], v[32:47]
	s_and_b32 m0, s32, 7
	s_lshl_b32 m0, m0, 12
	s_add_i32 m0, m0, 0xc400
	s_nop 0
	global_load_lds_dwordx4 v[160:161], off
	v_mfma_f32_32x32x16_bf16 v[16:31], a[0:3], a[12:15], v[16:31]
	v_mfma_f32_32x32x16_bf16 v[0:15], a[4:7], a[12:15], v[0:15]
	s_and_b32 m0, s32, 7
	s_lshl_b32 m0, m0, 12
	s_add_i32 m0, m0, 0xc800
	s_nop 0
	global_load_lds_dwordx4 v[162:163], off
	s_nop 0
	s_nop 0
	s_nop 0
	s_nop 0
	ds_read_b128 a[0:3], v106
	ds_read_b128 a[4:7], v107
	ds_read_b128 a[8:11], v108
	ds_read_b128 a[12:15], v109
	s_waitcnt lgkmcnt(5)
	v_mfma_f32_32x32x16_bf16 v[48:63], a[16:19], a[24:27], v[48:63]
	v_mfma_f32_32x32x16_bf16 v[32:47], a[20:23], a[24:27], v[32:47]
	s_and_b32 m0, s32, 7
	s_lshl_b32 m0, m0, 12
	s_add_i32 m0, m0, 0xcc00
	s_nop 0
	global_load_lds_dwordx4 v[164:165], off
	s_waitcnt lgkmcnt(4)
	v_mfma_f32_32x32x16_bf16 v[16:31], a[16:19], a[28:31], v[16:31]
	v_mfma_f32_32x32x16_bf16 v[0:15], a[20:23], a[28:31], v[0:15]
	s_and_b32 m0, s32, 7
	s_lshl_b32 m0, m0, 11
	s_add_i32 m0, m0, 0x14000
	s_nop 0
	global_load_lds_dwordx4 v[166:167], off
	s_nop 0
	s_nop 0
	s_nop 0
	s_nop 0
	ds_read_b128 a[16:19], v110
	ds_read_b128 a[20:23], v111
	ds_read_b128 a[24:27], v112
	ds_read_b128 a[28:31], v113
	s_waitcnt lgkmcnt(5)
	v_mfma_f32_32x32x16_bf16 v[48:63], a[0:3], a[8:11], v[48:63]
	v_mfma_f32_32x32x16_bf16 v[32:47], a[4:7], a[8:11], v[32:47]
	s_and_b32 m0, s32, 7
	s_lshl_b32 m0, m0, 11
	s_add_i32 m0, m0, 0x14400
	s_nop 0
	global_load_lds_dwordx4 v[168:169], off
	s_waitcnt lgkmcnt(4)
	v_mfma_f32_32x32x16_bf16 v[16:31], a[0:3], a[12:15], v[16:31]
	v_mfma_f32_32x32x16_bf16 v[0:15], a[4:7], a[12:15], v[0:15]
	s_nop 0
	s_nop 0
	s_nop 0
	s_nop 0
	s_waitcnt lgkmcnt(1)
	v_mfma_f32_32x32x16_bf16 v[48:63], a[16:19], a[24:27], v[48:63]
	v_mfma_f32_32x32x16_bf16 v[32:47], a[20:23], a[24:27], v[32:47]
	s_waitcnt vmcnt(6)
	s_waitcnt lgkmcnt(0)
	s_barrier
	ds_read_b128 a[12:15], v82 offset:4096
	ds_read_b128 a[8:11], v82
	ds_read_b128 a[4:7], v83 offset:36864
	ds_read_b128 a[0:3], v83 offset:32768
	v_mfma_f32_32x32x16_bf16 v[16:31], a[16:19], a[28:31], v[16:31]
	v_lshl_add_u64 v[170:171], v[66:67], 0, s[28:29]
	s_nop 0
	v_lshl_add_u64 v[172:173], v[68:69], 0, s[28:29]
	s_nop 0
	v_readfirstlane_b32 s1, v127
	s_nop 0
	v_lshl_add_u64 v[174:175], v[70:71], 0, s[28:29]
	s_nop 0
	v_mfma_f32_32x32x16_bf16 v[0:15], a[20:23], a[28:31], v[0:15]
	s_and_b32 m0, s32, 7
	s_lshl_b32 m0, m0, 12
	s_add_i32 m0, m0, 0x18000
	s_nop 0
	global_load_lds_dwordx4 v[170:171], off
	s_nop 0
	v_lshl_add_u64 v[176:177], v[72:73], 0, s[28:29]
	s_nop 0
	v_readfirstlane_b32 s20, v128
	s_nop 0
	v_lshl_add_u64 v[178:179], v[74:75], 0, s[28:29]
	s_nop 0
	v_readfirstlane_b32 s21, v129
	s_nop 0
	v_lshl_add_u64 v[180:181], v[76:77], 0, s[28:29]
	s_nop 0
	s_mov_b64 s[28:29], 0x480
	s_nop 0
	s_nop 0
	s_nop 0
	s_nop 0
	s_nop 0
	ds_read_b128 a[16:19], v85 offset:32768
	ds_read_b128 a[20:23], v85 offset:36864
	ds_read_b128 a[24:27], v84
	ds_read_b128 a[28:31], v84 offset:4096
	s_waitcnt lgkmcnt(4)
	v_mfma_f32_32x32x16_bf16 v[48:63], a[0:3], a[8:11], v[48:63]
	s_nop 0
	v_lshl_add_u64 v[162:163], v[70:71], 0, s[28:29]
	v_readfirstlane_b32 s23, v131
	v_readfirstlane_b32 s24, v130
	v_mfma_f32_32x32x16_bf16 v[32:47], a[4:7], a[8:11], v[32:47]
	s_and_b32 m0, s32, 7
	s_lshl_b32 m0, m0, 12
	s_add_i32 m0, m0, 0x18400
	s_nop 0
	global_load_lds_dwordx4 v[172:173], off
	v_mfma_f32_32x32x16_bf16 v[16:31], a[0:3], a[12:15], v[16:31]
	v_mfma_f32_32x32x16_bf16 v[0:15], a[4:7], a[12:15], v[0:15]
	s_and_b32 m0, s32, 7
	s_lshl_b32 m0, m0, 12
	s_add_i32 m0, m0, 0x18800
	s_nop 0
	global_load_lds_dwordx4 v[174:175], off
	s_nop 0
	s_nop 0
	s_nop 0
	s_nop 0
	ds_read_b128 a[0:3], v87 offset:32768
	ds_read_b128 a[4:7], v87 offset:36864
	ds_read_b128 a[8:11], v86
	ds_read_b128 a[12:15], v86 offset:4096
	s_waitcnt lgkmcnt(5)
	v_mfma_f32_32x32x16_bf16 v[48:63], a[16:19], a[24:27], v[48:63]
	v_mfma_f32_32x32x16_bf16 v[32:47], a[20:23], a[24:27], v[32:47]
	s_and_b32 m0, s32, 7
	s_lshl_b32 m0, m0, 12
	s_add_i32 m0, m0, 0x18c00
	s_nop 0
	global_load_lds_dwordx4 v[176:177], off
	s_waitcnt lgkmcnt(4)
	v_mfma_f32_32x32x16_bf16 v[16:31], a[16:19], a[28:31], v[16:31]
	v_mfma_f32_32x32x16_bf16 v[0:15], a[20:23], a[28:31], v[0:15]
	s_and_b32 m0, s32, 7
	s_lshl_b32 m0, m0, 11
	s_add_i32 m0, m0, 0x20000
	s_nop 0
	global_load_lds_dwordx4 v[178:179], off
	s_nop 0
	s_nop 0
	s_nop 0
	s_nop 0
	ds_read_b128 a[16:19], v89 offset:32768
	ds_read_b128 a[20:23], v89 offset:36864
	ds_read_b128 a[24:27], v88
	ds_read_b128 a[28:31], v88 offset:4096
	s_waitcnt lgkmcnt(5)
	v_mfma_f32_32x32x16_bf16 v[48:63], a[0:3], a[8:11], v[48:63]
	v_mfma_f32_32x32x16_bf16 v[32:47], a[4:7], a[8:11], v[32:47]
	s_and_b32 m0, s32, 7
	s_lshl_b32 m0, m0, 11
	s_add_i32 m0, m0, 0x20400
	s_nop 0
	global_load_lds_dwordx4 v[180:181], off
	s_waitcnt lgkmcnt(4)
	v_mfma_f32_32x32x16_bf16 v[16:31], a[0:3], a[12:15], v[16:31]
	v_mfma_f32_32x32x16_bf16 v[0:15], a[4:7], a[12:15], v[0:15]
	s_nop 0
	s_nop 0
	s_nop 0
	s_nop 0
	s_waitcnt lgkmcnt(1)
	v_mfma_f32_32x32x16_bf16 v[48:63], a[16:19], a[24:27], v[48:63]
	v_mfma_f32_32x32x16_bf16 v[32:47], a[20:23], a[24:27], v[32:47]
	s_waitcnt vmcnt(6)
	s_waitcnt lgkmcnt(0)
	s_barrier
	ds_read_b128 a[12:15], v82 offset:53248
	ds_read_b128 a[8:11], v82 offset:49152
	ds_read_b128 a[4:7], v90
	ds_read_b128 a[0:3], v92
	v_mfma_f32_32x32x16_bf16 v[16:31], a[16:19], a[28:31], v[16:31]
	v_lshl_add_u64 v[158:159], v[66:67], 0, s[28:29]
	s_nop 0
	v_lshl_add_u64 v[160:161], v[68:69], 0, s[28:29]
	s_nop 0
	s_nop 0
	s_nop 0
	s_nop 0
	v_mfma_f32_32x32x16_bf16 v[0:15], a[20:23], a[28:31], v[0:15]
	s_and_b32 m0, s32, 7
	s_lshl_b32 m0, m0, 12
	s_add_i32 m0, m0, 0x0
	s_nop 0
	global_load_lds_dwordx4 v[158:159], off
	s_nop 0
	v_lshl_add_u64 v[164:165], v[72:73], 0, s[28:29]
	s_nop 0
	s_nop 0
	s_nop 0
	v_lshl_add_u64 v[166:167], v[74:75], 0, s[28:29]
	s_nop 0
	s_nop 0
	s_nop 0
	v_lshl_add_u64 v[168:169], v[76:77], 0, s[28:29]
	s_nop 0
	v_readfirstlane_b32 s28, v120
	s_nop 0
	s_nop 0
	s_nop 0
	s_nop 0
	s_nop 0
	ds_read_b128 a[16:19], v93
	ds_read_b128 a[20:23], v91
	ds_read_b128 a[24:27], v84 offset:49152
	ds_read_b128 a[28:31], v84 offset:53248
	s_waitcnt lgkmcnt(4)
	v_mfma_f32_32x32x16_bf16 v[48:63], a[0:3], a[8:11], v[48:63]
	s_nop 0
	v_readfirstlane_b32 s29, v121
	v_lshl_add_u64 v[174:175], v[70:71], 0, s[36:37]
	v_mfma_f32_32x32x16_bf16 v[32:47], a[4:7], a[8:11], v[32:47]
	s_and_b32 m0, s32, 7
	s_lshl_b32 m0, m0, 12
	s_add_i32 m0, m0, 0x400
	s_nop 0
	global_load_lds_dwordx4 v[160:161], off
	v_mfma_f32_32x32x16_bf16 v[16:31], a[0:3], a[12:15], v[16:31]
	v_mfma_f32_32x32x16_bf16 v[0:15], a[4:7], a[12:15], v[0:15]
	s_and_b32 m0, s32, 7
	s_lshl_b32 m0, m0, 12
	s_add_i32 m0, m0, 0x800
	s_nop 0
	global_load_lds_dwordx4 v[162:163], off
	s_nop 0
	s_nop 0
	s_nop 0
	s_nop 0
	ds_read_b128 a[0:3], v95
	ds_read_b128 a[4:7], v94
	ds_read_b128 a[8:11], v86 offset:49152
	ds_read_b128 a[12:15], v86 offset:53248
	s_waitcnt lgkmcnt(5)
	v_mfma_f32_32x32x16_bf16 v[48:63], a[16:19], a[24:27], v[48:63]
	v_mfma_f32_32x32x16_bf16 v[32:47], a[20:23], a[24:27], v[32:47]
	s_and_b32 m0, s32, 7
	s_lshl_b32 m0, m0, 12
	s_add_i32 m0, m0, 0xc00
	s_nop 0
	global_load_lds_dwordx4 v[164:165], off
	s_waitcnt lgkmcnt(4)
	v_mfma_f32_32x32x16_bf16 v[16:31], a[16:19], a[28:31], v[16:31]
	v_mfma_f32_32x32x16_bf16 v[0:15], a[20:23], a[28:31], v[0:15]
	s_and_b32 m0, s32, 7
	s_lshl_b32 m0, m0, 11
	s_add_i32 m0, m0, 0x8000
	s_nop 0
	global_load_lds_dwordx4 v[166:167], off
	s_nop 0
	s_nop 0
	s_nop 0
	s_nop 0
	ds_read_b128 a[16:19], v97
	ds_read_b128 a[20:23], v96
	ds_read_b128 a[24:27], v88 offset:49152
	ds_read_b128 a[28:31], v88 offset:53248
	s_waitcnt lgkmcnt(5)
	v_mfma_f32_32x32x16_bf16 v[48:63], a[0:3], a[8:11], v[48:63]
	v_mfma_f32_32x32x16_bf16 v[32:47], a[4:7], a[8:11], v[32:47]
	s_and_b32 m0, s32, 7
	s_lshl_b32 m0, m0, 11
	s_add_i32 m0, m0, 0x8400
	s_nop 0
	global_load_lds_dwordx4 v[168:169], off
	s_waitcnt lgkmcnt(4)
	v_mfma_f32_32x32x16_bf16 v[16:31], a[0:3], a[12:15], v[16:31]
	v_mfma_f32_32x32x16_bf16 v[0:15], a[4:7], a[12:15], v[0:15]
	s_nop 0
	s_nop 0
	s_nop 0
	s_nop 0
	s_waitcnt lgkmcnt(1)
	v_mfma_f32_32x32x16_bf16 v[48:63], a[16:19], a[24:27], v[48:63]
	v_mfma_f32_32x32x16_bf16 v[32:47], a[20:23], a[24:27], v[32:47]
	s_waitcnt vmcnt(6)
	s_waitcnt lgkmcnt(0)
	s_barrier
	ds_read_b128 a[12:15], v101
	ds_read_b128 a[8:11], v100
	ds_read_b128 a[4:7], v99
	ds_read_b128 a[0:3], v98
	v_mfma_f32_32x32x16_bf16 v[16:31], a[16:19], a[28:31], v[16:31]
	v_lshl_add_u64 v[170:171], v[66:67], 0, s[36:37]
	s_nop 0
	v_lshl_add_u64 v[172:173], v[68:69], 0, s[36:37]
	s_nop 0
	s_nop 0
	s_nop 0
	s_nop 0
	v_mfma_f32_32x32x16_bf16 v[0:15], a[20:23], a[28:31], v[0:15]
	s_and_b32 m0, s32, 7
	s_lshl_b32 m0, m0, 12
	s_add_i32 m0, m0, 0xc000
	s_nop 0
	global_load_lds_dwordx4 v[170:171], off
	s_nop 0
	v_lshl_add_u64 v[176:177], v[72:73], 0, s[36:37]
	s_nop 0
	s_nop 0
	s_nop 0
	v_lshl_add_u64 v[178:179], v[74:75], 0, s[36:37]
	s_nop 0
	s_nop 0
	s_nop 0
	v_lshl_add_u64 v[180:181], v[76:77], 0, s[36:37]
	v_readfirstlane_b32 s36, v125
	s_nop 0
	v_readfirstlane_b32 s37, v114
	s_nop 0
	s_nop 0
	s_nop 0
	s_nop 0
	s_nop 0
	ds_read_b128 a[16:19], v102
	ds_read_b128 a[20:23], v103
	ds_read_b128 a[24:27], v104
	ds_read_b128 a[28:31], v105
	s_waitcnt lgkmcnt(4)
	v_mfma_f32_32x32x16_bf16 v[48:63], a[0:3], a[8:11], v[48:63]
	s_nop 0
	v_lshl_add_u64 v[162:163], v[70:71], 0, s[46:47]
	v_mfma_f32_32x32x16_bf16 v[32:47], a[4:7], a[8:11], v[32:47]
	s_and_b32 m0, s32, 7
	s_lshl_b32 m0, m0, 12
	s_add_i32 m0, m0, 0xc400
	s_nop 0
	global_load_lds_dwordx4 v[172:173], off
	v_mfma_f32_32x32x16_bf16 v[16:31], a[0:3], a[12:15], v[16:31]
	v_mfma_f32_32x32x16_bf16 v[0:15], a[4:7], a[12:15], v[0:15]
	s_and_b32 m0, s32, 7
	s_lshl_b32 m0, m0, 12
	s_add_i32 m0, m0, 0xc800
	s_nop 0
	global_load_lds_dwordx4 v[174:175], off
	s_nop 0
	s_nop 0
	s_nop 0
	s_nop 0
	ds_read_b128 a[0:3], v106
	ds_read_b128 a[4:7], v107
	ds_read_b128 a[8:11], v108
	ds_read_b128 a[12:15], v109
	s_waitcnt lgkmcnt(5)
	v_mfma_f32_32x32x16_bf16 v[48:63], a[16:19], a[24:27], v[48:63]
	v_mfma_f32_32x32x16_bf16 v[32:47], a[20:23], a[24:27], v[32:47]
	s_and_b32 m0, s32, 7
	s_lshl_b32 m0, m0, 12
	s_add_i32 m0, m0, 0xcc00
	s_nop 0
	global_load_lds_dwordx4 v[176:177], off
	s_waitcnt lgkmcnt(4)
	v_mfma_f32_32x32x16_bf16 v[16:31], a[16:19], a[28:31], v[16:31]
	v_mfma_f32_32x32x16_bf16 v[0:15], a[20:23], a[28:31], v[0:15]
	s_and_b32 m0, s32, 7
	s_lshl_b32 m0, m0, 11
	s_add_i32 m0, m0, 0x14000
	s_nop 0
	global_load_lds_dwordx4 v[178:179], off
	s_nop 0
	s_nop 0
	s_nop 0
	s_nop 0
	ds_read_b128 a[16:19], v110
	ds_read_b128 a[20:23], v111
	ds_read_b128 a[24:27], v112
	ds_read_b128 a[28:31], v113
	s_waitcnt lgkmcnt(5)
	v_mfma_f32_32x32x16_bf16 v[48:63], a[0:3], a[8:11], v[48:63]
	v_mfma_f32_32x32x16_bf16 v[32:47], a[4:7], a[8:11], v[32:47]
	s_and_b32 m0, s32, 7
	s_lshl_b32 m0, m0, 11
	s_add_i32 m0, m0, 0x14400
	s_nop 0
	global_load_lds_dwordx4 v[180:181], off
	s_waitcnt lgkmcnt(4)
	v_mfma_f32_32x32x16_bf16 v[16:31], a[0:3], a[12:15], v[16:31]
	v_mfma_f32_32x32x16_bf16 v[0:15], a[4:7], a[12:15], v[0:15]
	s_nop 0
	s_nop 0
	s_nop 0
	s_nop 0
	s_waitcnt lgkmcnt(1)
	v_mfma_f32_32x32x16_bf16 v[48:63], a[16:19], a[24:27], v[48:63]
	v_mfma_f32_32x32x16_bf16 v[32:47], a[20:23], a[24:27], v[32:47]
	s_waitcnt vmcnt(6)
	s_waitcnt lgkmcnt(0)
	s_barrier
	ds_read_b128 a[12:15], v82 offset:4096
	ds_read_b128 a[8:11], v82
	ds_read_b128 a[4:7], v83 offset:36864
	ds_read_b128 a[0:3], v83 offset:32768
	v_mfma_f32_32x32x16_bf16 v[16:31], a[16:19], a[28:31], v[16:31]
	v_lshl_add_u64 v[158:159], v[66:67], 0, s[46:47]
	s_nop 0
	v_lshl_add_u64 v[160:161], v[68:69], 0, s[46:47]
	s_nop 0
	s_nop 0
	s_nop 0
	s_nop 0
	v_mfma_f32_32x32x16_bf16 v[0:15], a[20:23], a[28:31], v[0:15]
	s_and_b32 m0, s32, 7
	s_lshl_b32 m0, m0, 12
	s_add_i32 m0, m0, 0x18000
	s_nop 0
	global_load_lds_dwordx4 v[158:159], off
	s_nop 0
	v_lshl_add_u64 v[164:165], v[72:73], 0, s[46:47]
	s_nop 0
	s_nop 0
	s_nop 0
	v_lshl_add_u64 v[166:167], v[74:75], 0, s[46:47]
	s_nop 0
	s_nop 0
	s_nop 0
	v_lshl_add_u64 v[168:169], v[76:77], 0, s[46:47]
	s_nop 0
	s_mov_b64 s[46:47], 0x600
	s_nop 0
	s_nop 0
	s_nop 0
	s_nop 0
	s_nop 0
	ds_read_b128 a[16:19], v85 offset:32768
	ds_read_b128 a[20:23], v85 offset:36864
	ds_read_b128 a[24:27], v84
	ds_read_b128 a[28:31], v84 offset:4096
	s_waitcnt lgkmcnt(4)
	v_mfma_f32_32x32x16_bf16 v[48:63], a[0:3], a[8:11], v[48:63]
	s_nop 0
	v_mfma_f32_32x32x16_bf16 v[32:47], a[4:7], a[8:11], v[32:47]
	s_and_b32 m0, s32, 7
	s_lshl_b32 m0, m0, 12
	s_add_i32 m0, m0, 0x18400
	s_nop 0
	global_load_lds_dwordx4 v[160:161], off
	v_mfma_f32_32x32x16_bf16 v[16:31], a[0:3], a[12:15], v[16:31]
	v_mfma_f32_32x32x16_bf16 v[0:15], a[4:7], a[12:15], v[0:15]
	s_and_b32 m0, s32, 7
	s_lshl_b32 m0, m0, 12
	s_add_i32 m0, m0, 0x18800
	s_nop 0
	global_load_lds_dwordx4 v[162:163], off
	s_nop 0
	s_nop 0
	s_nop 0
	s_nop 0
	ds_read_b128 a[0:3], v87 offset:32768
	ds_read_b128 a[4:7], v87 offset:36864
	ds_read_b128 a[8:11], v86
	ds_read_b128 a[12:15], v86 offset:4096
	s_waitcnt lgkmcnt(5)
	v_mfma_f32_32x32x16_bf16 v[48:63], a[16:19], a[24:27], v[48:63]
	v_mfma_f32_32x32x16_bf16 v[32:47], a[20:23], a[24:27], v[32:47]
	s_and_b32 m0, s32, 7
	s_lshl_b32 m0, m0, 12
	s_add_i32 m0, m0, 0x18c00
	s_nop 0
	global_load_lds_dwordx4 v[164:165], off
	s_waitcnt lgkmcnt(4)
	v_mfma_f32_32x32x16_bf16 v[16:31], a[16:19], a[28:31], v[16:31]
	v_mfma_f32_32x32x16_bf16 v[0:15], a[20:23], a[28:31], v[0:15]
	s_and_b32 m0, s32, 7
	s_lshl_b32 m0, m0, 11
	s_add_i32 m0, m0, 0x20000
	s_nop 0
	global_load_lds_dwordx4 v[166:167], off
	s_nop 0
	s_nop 0
	s_nop 0
	s_nop 0
	ds_read_b128 a[16:19], v89 offset:32768
	ds_read_b128 a[20:23], v89 offset:36864
	ds_read_b128 a[24:27], v88
	ds_read_b128 a[28:31], v88 offset:4096
	s_waitcnt lgkmcnt(5)
	v_mfma_f32_32x32x16_bf16 v[48:63], a[0:3], a[8:11], v[48:63]
	v_mfma_f32_32x32x16_bf16 v[32:47], a[4:7], a[8:11], v[32:47]
	s_and_b32 m0, s32, 7
	s_lshl_b32 m0, m0, 11
	s_add_i32 m0, m0, 0x20400
	s_nop 0
	global_load_lds_dwordx4 v[168:169], off
	s_waitcnt lgkmcnt(4)
	v_mfma_f32_32x32x16_bf16 v[16:31], a[0:3], a[12:15], v[16:31]
	v_mfma_f32_32x32x16_bf16 v[0:15], a[4:7], a[12:15], v[0:15]
	s_nop 0
	s_nop 0
	s_nop 0
	s_nop 0
	s_waitcnt lgkmcnt(1)
	v_mfma_f32_32x32x16_bf16 v[48:63], a[16:19], a[24:27], v[48:63]
	v_mfma_f32_32x32x16_bf16 v[32:47], a[20:23], a[24:27], v[32:47]
	s_waitcnt vmcnt(6)
	s_waitcnt lgkmcnt(0)
	s_barrier
	ds_read_b128 a[12:15], v82 offset:53248
	ds_read_b128 a[8:11], v82 offset:49152
	ds_read_b128 a[4:7], v90
	ds_read_b128 a[0:3], v92
	v_mfma_f32_32x32x16_bf16 v[16:31], a[16:19], a[28:31], v[16:31]
	v_lshl_add_u64 v[170:171], v[66:67], 0, s[46:47]
	s_nop 0
	v_lshl_add_u64 v[172:173], v[68:69], 0, s[46:47]
	s_nop 0
	s_nop 0
	s_nop 0
	v_lshl_add_u64 v[174:175], v[70:71], 0, s[46:47]
	s_nop 0
	v_mfma_f32_32x32x16_bf16 v[0:15], a[20:23], a[28:31], v[0:15]
	s_and_b32 m0, s32, 7
	s_lshl_b32 m0, m0, 12
	s_add_i32 m0, m0, 0x0
	s_nop 0
	global_load_lds_dwordx4 v[170:171], off
	s_nop 0
	v_lshl_add_u64 v[176:177], v[72:73], 0, s[46:47]
	s_nop 0
	s_nop 0
	s_nop 0
	v_lshl_add_u64 v[178:179], v[74:75], 0, s[46:47]
	s_nop 0
	s_nop 0
	s_nop 0
	v_lshl_add_u64 v[180:181], v[76:77], 0, s[46:47]
	s_nop 0
	s_mov_b64 s[46:47], 0x680
	s_nop 0
	s_nop 0
	s_nop 0
	s_nop 0
	s_nop 0
	ds_read_b128 a[16:19], v93
	ds_read_b128 a[20:23], v91
	ds_read_b128 a[24:27], v84 offset:49152
	ds_read_b128 a[28:31], v84 offset:53248
	s_waitcnt lgkmcnt(4)
	v_mfma_f32_32x32x16_bf16 v[48:63], a[0:3], a[8:11], v[48:63]
	s_nop 0
	v_mfma_f32_32x32x16_bf16 v[32:47], a[4:7], a[8:11], v[32:47]
	s_and_b32 m0, s32, 7
	s_lshl_b32 m0, m0, 12
	s_add_i32 m0, m0, 0x400
	s_nop 0
	global_load_lds_dwordx4 v[172:173], off
	v_mfma_f32_32x32x16_bf16 v[16:31], a[0:3], a[12:15], v[16:31]
	v_mfma_f32_32x32x16_bf16 v[0:15], a[4:7], a[12:15], v[0:15]
	s_and_b32 m0, s32, 7
	s_lshl_b32 m0, m0, 12
	s_add_i32 m0, m0, 0x800
	s_nop 0
	global_load_lds_dwordx4 v[174:175], off
	s_nop 0
	s_nop 0
	s_nop 0
	s_nop 0
	ds_read_b128 a[0:3], v95
	ds_read_b128 a[4:7], v94
	ds_read_b128 a[8:11], v86 offset:49152
	ds_read_b128 a[12:15], v86 offset:53248
	s_waitcnt lgkmcnt(5)
	v_mfma_f32_32x32x16_bf16 v[48:63], a[16:19], a[24:27], v[48:63]
	v_mfma_f32_32x32x16_bf16 v[32:47], a[20:23], a[24:27], v[32:47]
	s_and_b32 m0, s32, 7
	s_lshl_b32 m0, m0, 12
	s_add_i32 m0, m0, 0xc00
	s_nop 0
	global_load_lds_dwordx4 v[176:177], off
	s_waitcnt lgkmcnt(4)
	v_mfma_f32_32x32x16_bf16 v[16:31], a[16:19], a[28:31], v[16:31]
	v_mfma_f32_32x32x16_bf16 v[0:15], a[20:23], a[28:31], v[0:15]
	s_and_b32 m0, s32, 7
	s_lshl_b32 m0, m0, 11
	s_add_i32 m0, m0, 0x8000
	s_nop 0
	global_load_lds_dwordx4 v[178:179], off
	s_nop 0
	s_nop 0
	s_nop 0
	s_nop 0
	ds_read_b128 a[16:19], v97
	ds_read_b128 a[20:23], v96
	ds_read_b128 a[24:27], v88 offset:49152
	ds_read_b128 a[28:31], v88 offset:53248
	s_waitcnt lgkmcnt(5)
	v_mfma_f32_32x32x16_bf16 v[48:63], a[0:3], a[8:11], v[48:63]
	v_mfma_f32_32x32x16_bf16 v[32:47], a[4:7], a[8:11], v[32:47]
	s_and_b32 m0, s32, 7
	s_lshl_b32 m0, m0, 11
	s_add_i32 m0, m0, 0x8400
	s_nop 0
	global_load_lds_dwordx4 v[180:181], off
	s_waitcnt lgkmcnt(4)
	v_mfma_f32_32x32x16_bf16 v[16:31], a[0:3], a[12:15], v[16:31]
	v_mfma_f32_32x32x16_bf16 v[0:15], a[4:7], a[12:15], v[0:15]
	s_nop 0
	s_nop 0
	s_nop 0
	s_nop 0
	s_waitcnt lgkmcnt(1)
	v_mfma_f32_32x32x16_bf16 v[48:63], a[16:19], a[24:27], v[48:63]
	v_mfma_f32_32x32x16_bf16 v[32:47], a[20:23], a[24:27], v[32:47]
	s_waitcnt vmcnt(6)
	s_waitcnt lgkmcnt(0)
	s_barrier
	ds_read_b128 a[12:15], v101
	ds_read_b128 a[8:11], v100
	ds_read_b128 a[4:7], v99
	ds_read_b128 a[0:3], v98
	v_mfma_f32_32x32x16_bf16 v[16:31], a[16:19], a[28:31], v[16:31]
	v_lshl_add_u64 v[158:159], v[66:67], 0, s[46:47]
	s_nop 0
	v_lshl_add_u64 v[160:161], v[68:69], 0, s[46:47]
	s_nop 0
	s_mov_b64 s[28:29], 0x700
	s_nop 0
	v_lshl_add_u64 v[162:163], v[70:71], 0, s[46:47]
	s_nop 0
	v_mfma_f32_32x32x16_bf16 v[0:15], a[20:23], a[28:31], v[0:15]
	s_and_b32 m0, s32, 7
	s_lshl_b32 m0, m0, 12
	s_add_i32 m0, m0, 0xc000
	s_nop 0
	global_load_lds_dwordx4 v[158:159], off
	s_nop 0
	v_lshl_add_u64 v[164:165], v[72:73], 0, s[46:47]
	s_nop 0
	s_nop 0
	s_nop 0
	v_lshl_add_u64 v[166:167], v[74:75], 0, s[46:47]
	s_nop 0
	s_nop 0
	s_nop 0
	v_lshl_add_u64 v[168:169], v[76:77], 0, s[46:47]
	s_nop 0
	s_nop 0
	s_nop 0
	s_nop 0
	s_nop 0
	s_nop 0
	s_nop 0
	ds_read_b128 a[16:19], v102
	ds_read_b128 a[20:23], v103
	ds_read_b128 a[24:27], v104
	ds_read_b128 a[28:31], v105
	s_waitcnt lgkmcnt(4)
	v_mfma_f32_32x32x16_bf16 v[48:63], a[0:3], a[8:11], v[48:63]
	s_nop 0
	v_mfma_f32_32x32x16_bf16 v[32:47], a[4:7], a[8:11], v[32:47]
	s_and_b32 m0, s32, 7
	s_lshl_b32 m0, m0, 12
	s_add_i32 m0, m0, 0xc400
	s_nop 0
	global_load_lds_dwordx4 v[160:161], off
	v_mfma_f32_32x32x16_bf16 v[16:31], a[0:3], a[12:15], v[16:31]
	v_mfma_f32_32x32x16_bf16 v[0:15], a[4:7], a[12:15], v[0:15]
	s_and_b32 m0, s32, 7
	s_lshl_b32 m0, m0, 12
	s_add_i32 m0, m0, 0xc800
	s_nop 0
	global_load_lds_dwordx4 v[162:163], off
	s_nop 0
	s_nop 0
	s_nop 0
	s_nop 0
	ds_read_b128 a[0:3], v106
	ds_read_b128 a[4:7], v107
	ds_read_b128 a[8:11], v108
	ds_read_b128 a[12:15], v109
	s_waitcnt lgkmcnt(5)
	v_mfma_f32_32x32x16_bf16 v[48:63], a[16:19], a[24:27], v[48:63]
	v_mfma_f32_32x32x16_bf16 v[32:47], a[20:23], a[24:27], v[32:47]
	s_and_b32 m0, s32, 7
	s_lshl_b32 m0, m0, 12
	s_add_i32 m0, m0, 0xcc00
	s_nop 0
	global_load_lds_dwordx4 v[164:165], off
	s_waitcnt lgkmcnt(4)
	v_mfma_f32_32x32x16_bf16 v[16:31], a[16:19], a[28:31], v[16:31]
	v_mfma_f32_32x32x16_bf16 v[0:15], a[20:23], a[28:31], v[0:15]
	s_and_b32 m0, s32, 7
	s_lshl_b32 m0, m0, 11
	s_add_i32 m0, m0, 0x14000
	s_nop 0
	global_load_lds_dwordx4 v[166:167], off
	s_nop 0
	s_nop 0
	s_nop 0
	s_nop 0
	ds_read_b128 a[16:19], v110
	ds_read_b128 a[20:23], v111
	ds_read_b128 a[24:27], v112
	ds_read_b128 a[28:31], v113
	s_waitcnt lgkmcnt(5)
	v_mfma_f32_32x32x16_bf16 v[48:63], a[0:3], a[8:11], v[48:63]
	v_mfma_f32_32x32x16_bf16 v[32:47], a[4:7], a[8:11], v[32:47]
	s_and_b32 m0, s32, 7
	s_lshl_b32 m0, m0, 11
	s_add_i32 m0, m0, 0x14400
	s_nop 0
	global_load_lds_dwordx4 v[168:169], off
	s_waitcnt lgkmcnt(4)
	v_mfma_f32_32x32x16_bf16 v[16:31], a[0:3], a[12:15], v[16:31]
	v_mfma_f32_32x32x16_bf16 v[0:15], a[4:7], a[12:15], v[0:15]
	s_nop 0
	s_nop 0
	s_nop 0
	s_nop 0
	s_waitcnt lgkmcnt(1)
	v_mfma_f32_32x32x16_bf16 v[48:63], a[16:19], a[24:27], v[48:63]
	v_mfma_f32_32x32x16_bf16 v[32:47], a[20:23], a[24:27], v[32:47]
	s_waitcnt vmcnt(6)
	s_waitcnt lgkmcnt(0)
	s_barrier
	ds_read_b128 a[12:15], v82 offset:4096
	ds_read_b128 a[8:11], v82
	ds_read_b128 a[4:7], v83 offset:36864
	ds_read_b128 a[0:3], v83 offset:32768
	v_mfma_f32_32x32x16_bf16 v[16:31], a[16:19], a[28:31], v[16:31]
	v_lshl_add_u64 v[170:171], v[66:67], 0, s[28:29]
	s_nop 0
	v_lshl_add_u64 v[172:173], v[68:69], 0, s[28:29]
	s_nop 0
	s_nop 0
	s_nop 0
	v_lshl_add_u64 v[174:175], v[70:71], 0, s[28:29]
	s_nop 0
	v_mfma_f32_32x32x16_bf16 v[0:15], a[20:23], a[28:31], v[0:15]
	s_and_b32 m0, s32, 7
	s_lshl_b32 m0, m0, 12
	s_add_i32 m0, m0, 0x18000
	s_nop 0
	global_load_lds_dwordx4 v[170:171], off
	s_nop 0
	v_lshl_add_u64 v[176:177], v[72:73], 0, s[28:29]
	s_nop 0
	s_nop 0
	s_nop 0
	v_lshl_add_u64 v[178:179], v[74:75], 0, s[28:29]
	s_nop 0
	s_nop 0
	s_nop 0
	v_lshl_add_u64 v[180:181], v[76:77], 0, s[28:29]
	s_nop 0
	s_mov_b64 s[28:29], 0x780
	s_nop 0
	s_nop 0
	s_nop 0
	s_nop 0
	s_nop 0
	ds_read_b128 a[16:19], v85 offset:32768
	ds_read_b128 a[20:23], v85 offset:36864
	ds_read_b128 a[24:27], v84
	ds_read_b128 a[28:31], v84 offset:4096
	s_waitcnt lgkmcnt(4)
	v_mfma_f32_32x32x16_bf16 v[48:63], a[0:3], a[8:11], v[48:63]
	v_lshl_add_u64 v[158:159], v[66:67], 0, s[28:29]
	s_nop 0
	v_mfma_f32_32x32x16_bf16 v[32:47], a[4:7], a[8:11], v[32:47]
	s_and_b32 m0, s32, 7
	s_lshl_b32 m0, m0, 12
	s_add_i32 m0, m0, 0x18400
	s_nop 0
	global_load_lds_dwordx4 v[172:173], off
	v_mfma_f32_32x32x16_bf16 v[16:31], a[0:3], a[12:15], v[16:31]
	v_mfma_f32_32x32x16_bf16 v[0:15], a[4:7], a[12:15], v[0:15]
	s_and_b32 m0, s32, 7
	s_lshl_b32 m0, m0, 12
	s_add_i32 m0, m0, 0x18800
	s_nop 0
	global_load_lds_dwordx4 v[174:175], off
	s_nop 0
	s_nop 0
	s_nop 0
	s_nop 0
	ds_read_b128 a[0:3], v87 offset:32768
	ds_read_b128 a[4:7], v87 offset:36864
	ds_read_b128 a[8:11], v86
	ds_read_b128 a[12:15], v86 offset:4096
	s_waitcnt lgkmcnt(5)
	v_mfma_f32_32x32x16_bf16 v[48:63], a[16:19], a[24:27], v[48:63]
	v_mfma_f32_32x32x16_bf16 v[32:47], a[20:23], a[24:27], v[32:47]
	s_and_b32 m0, s32, 7
	s_lshl_b32 m0, m0, 12
	s_add_i32 m0, m0, 0x18c00
	s_nop 0
	global_load_lds_dwordx4 v[176:177], off
	s_waitcnt lgkmcnt(4)
	v_mfma_f32_32x32x16_bf16 v[16:31], a[16:19], a[28:31], v[16:31]
	v_mfma_f32_32x32x16_bf16 v[0:15], a[20:23], a[28:31], v[0:15]
	s_and_b32 m0, s32, 7
	s_lshl_b32 m0, m0, 11
	s_add_i32 m0, m0, 0x20000
	s_nop 0
	global_load_lds_dwordx4 v[178:179], off
	s_nop 0
	s_nop 0
	s_nop 0
	s_nop 0
	ds_read_b128 a[16:19], v89 offset:32768
	ds_read_b128 a[20:23], v89 offset:36864
	ds_read_b128 a[24:27], v88
	ds_read_b128 a[28:31], v88 offset:4096
	s_waitcnt lgkmcnt(5)
	v_mfma_f32_32x32x16_bf16 v[48:63], a[0:3], a[8:11], v[48:63]
	v_mfma_f32_32x32x16_bf16 v[32:47], a[4:7], a[8:11], v[32:47]
	s_and_b32 m0, s32, 7
	s_lshl_b32 m0, m0, 11
	s_add_i32 m0, m0, 0x20400
	s_nop 0
	global_load_lds_dwordx4 v[180:181], off
	s_waitcnt lgkmcnt(4)
	v_mfma_f32_32x32x16_bf16 v[16:31], a[0:3], a[12:15], v[16:31]
	v_mfma_f32_32x32x16_bf16 v[0:15], a[4:7], a[12:15], v[0:15]
	s_nop 0
	s_nop 0
	s_nop 0
	s_nop 0
	s_waitcnt lgkmcnt(1)
	v_mfma_f32_32x32x16_bf16 v[48:63], a[16:19], a[24:27], v[48:63]
	v_mfma_f32_32x32x16_bf16 v[32:47], a[20:23], a[24:27], v[32:47]
	s_waitcnt vmcnt(6)
	s_waitcnt lgkmcnt(0)
	s_barrier
	ds_read_b128 a[12:15], v82 offset:53248
	ds_read_b128 a[8:11], v82 offset:49152
	ds_read_b128 a[4:7], v90
	ds_read_b128 a[0:3], v92
	s_nop 0
	v_lshl_add_u64 v[160:161], v[68:69], 0, s[28:29]
	s_nop 0
	v_mfma_f32_32x32x16_bf16 v[16:31], a[16:19], a[28:31], v[16:31]
	s_nop 0
	v_lshl_add_u64 v[162:163], v[70:71], 0, s[28:29]
	s_nop 0
	v_cmp_eq_u32_e64 s[0:1], 0, v79
	s_nop 0
	v_lshl_add_u64 v[164:165], v[72:73], 0, s[28:29]
	s_nop 0
	v_mfma_f32_32x32x16_bf16 v[0:15], a[20:23], a[28:31], v[0:15]
	s_and_b32 m0, s32, 7
	s_lshl_b32 m0, m0, 12
	s_add_i32 m0, m0, 0x0
	s_nop 0
	global_load_lds_dwordx4 v[158:159], off
	s_nop 0
	v_lshl_add_u64 v[166:167], v[74:75], 0, s[28:29]
	s_nop 0
	v_readlane_b32 s20, v215, 52
	s_nop 0
	v_lshl_add_u64 v[168:169], v[76:77], 0, s[28:29]
	s_nop 0
	v_readlane_b32 s21, v215, 53
	s_nop 0
	s_nop 0
	s_nop 0
	s_nop 0
	s_nop 0
	ds_read_b128 a[16:19], v93
	ds_read_b128 a[20:23], v91
	ds_read_b128 a[24:27], v84 offset:49152
	ds_read_b128 a[28:31], v84 offset:53248
	s_waitcnt lgkmcnt(4)
	v_mfma_f32_32x32x16_bf16 v[48:63], a[0:3], a[8:11], v[48:63]
	s_mov_b32 s23, 0
	v_mfma_f32_32x32x16_bf16 v[32:47], a[4:7], a[8:11], v[32:47]
	s_and_b32 m0, s32, 7
	s_lshl_b32 m0, m0, 12
	s_add_i32 m0, m0, 0x400
	s_nop 0
	global_load_lds_dwordx4 v[160:161], off
	v_mfma_f32_32x32x16_bf16 v[16:31], a[0:3], a[12:15], v[16:31]
	v_mfma_f32_32x32x16_bf16 v[0:15], a[4:7], a[12:15], v[0:15]
	s_and_b32 m0, s32, 7
	s_lshl_b32 m0, m0, 12
	s_add_i32 m0, m0, 0x800
	s_nop 0
	global_load_lds_dwordx4 v[162:163], off
	s_nop 0
	s_nop 0
	s_nop 0
	s_nop 0
	ds_read_b128 a[0:3], v95
	ds_read_b128 a[4:7], v94
	ds_read_b128 a[8:11], v86 offset:49152
	ds_read_b128 a[12:15], v86 offset:53248
	s_waitcnt lgkmcnt(5)
	v_mfma_f32_32x32x16_bf16 v[48:63], a[16:19], a[24:27], v[48:63]
	v_mfma_f32_32x32x16_bf16 v[32:47], a[20:23], a[24:27], v[32:47]
	s_and_b32 m0, s32, 7
	s_lshl_b32 m0, m0, 12
	s_add_i32 m0, m0, 0xc00
	s_nop 0
	global_load_lds_dwordx4 v[164:165], off
	s_waitcnt lgkmcnt(4)
	v_mfma_f32_32x32x16_bf16 v[16:31], a[16:19], a[28:31], v[16:31]
	v_mfma_f32_32x32x16_bf16 v[0:15], a[20:23], a[28:31], v[0:15]
	s_and_b32 m0, s32, 7
	s_lshl_b32 m0, m0, 11
	s_add_i32 m0, m0, 0x8000
	s_nop 0
	global_load_lds_dwordx4 v[166:167], off
	s_nop 0
	s_nop 0
	s_nop 0
	s_nop 0
	ds_read_b128 a[16:19], v97
	ds_read_b128 a[20:23], v96
	ds_read_b128 a[24:27], v88 offset:49152
	ds_read_b128 a[28:31], v88 offset:53248
	s_waitcnt lgkmcnt(5)
	v_mfma_f32_32x32x16_bf16 v[48:63], a[0:3], a[8:11], v[48:63]
	v_mfma_f32_32x32x16_bf16 v[32:47], a[4:7], a[8:11], v[32:47]
	s_and_b32 m0, s32, 7
	s_lshl_b32 m0, m0, 11
	s_add_i32 m0, m0, 0x8400
	s_nop 0
	global_load_lds_dwordx4 v[168:169], off
	s_waitcnt lgkmcnt(4)
	v_mfma_f32_32x32x16_bf16 v[16:31], a[0:3], a[12:15], v[16:31]
	v_mfma_f32_32x32x16_bf16 v[0:15], a[4:7], a[12:15], v[0:15]
	s_nop 0
	s_nop 0
	s_nop 0
	s_nop 0
	s_waitcnt lgkmcnt(1)
	v_mfma_f32_32x32x16_bf16 v[48:63], a[16:19], a[24:27], v[48:63]
	v_mfma_f32_32x32x16_bf16 v[32:47], a[20:23], a[24:27], v[32:47]
	s_waitcnt vmcnt(6)
	s_waitcnt lgkmcnt(0)
	s_barrier
	ds_read_b128 a[12:15], v101
	ds_read_b128 a[8:11], v100
	ds_read_b128 a[4:7], v99
	ds_read_b128 a[0:3], v98
	v_mfma_f32_32x32x16_bf16 v[16:31], a[16:19], a[28:31], v[16:31]
	v_mfma_f32_32x32x16_bf16 v[0:15], a[20:23], a[28:31], v[0:15]
	s_nop 0
	s_nop 0
	s_nop 0
	s_nop 0
	ds_read_b128 a[16:19], v102
	ds_read_b128 a[20:23], v103
	ds_read_b128 a[24:27], v104
	ds_read_b128 a[28:31], v105
	s_waitcnt lgkmcnt(4)
	v_mfma_f32_32x32x16_bf16 v[48:63], a[0:3], a[8:11], v[48:63]
	v_mfma_f32_32x32x16_bf16 v[32:47], a[4:7], a[8:11], v[32:47]
	v_mfma_f32_32x32x16_bf16 v[16:31], a[0:3], a[12:15], v[16:31]
	v_mfma_f32_32x32x16_bf16 v[0:15], a[4:7], a[12:15], v[0:15]
	s_nop 0
	s_nop 0
	s_nop 0
	s_nop 0
	ds_read_b128 a[0:3], v106
	ds_read_b128 a[4:7], v107
	ds_read_b128 a[8:11], v108
	ds_read_b128 a[12:15], v109
	s_waitcnt lgkmcnt(5)
	v_mfma_f32_32x32x16_bf16 v[48:63], a[16:19], a[24:27], v[48:63]
	v_mfma_f32_32x32x16_bf16 v[32:47], a[20:23], a[24:27], v[32:47]
	s_waitcnt lgkmcnt(4)
	v_mfma_f32_32x32x16_bf16 v[16:31], a[16:19], a[28:31], v[16:31]
	v_mfma_f32_32x32x16_bf16 v[0:15], a[20:23], a[28:31], v[0:15]
	s_nop 0
	s_nop 0
	s_nop 0
	s_nop 0
	ds_read_b128 a[16:19], v110
	ds_read_b128 a[20:23], v111
	ds_read_b128 a[24:27], v112
	ds_read_b128 a[28:31], v113
	s_waitcnt lgkmcnt(5)
	v_mfma_f32_32x32x16_bf16 v[48:63], a[0:3], a[8:11], v[48:63]
	v_mfma_f32_32x32x16_bf16 v[32:47], a[4:7], a[8:11], v[32:47]
	s_waitcnt lgkmcnt(4)
	v_mfma_f32_32x32x16_bf16 v[16:31], a[0:3], a[12:15], v[16:31]
	v_mfma_f32_32x32x16_bf16 v[0:15], a[4:7], a[12:15], v[0:15]
	s_nop 0
	s_nop 0
	s_nop 0
	s_nop 0
	s_waitcnt lgkmcnt(1)
	v_mfma_f32_32x32x16_bf16 v[48:63], a[16:19], a[24:27], v[48:63]
	v_mfma_f32_32x32x16_bf16 v[32:47], a[20:23], a[24:27], v[32:47]
	s_waitcnt vmcnt(0)
	s_waitcnt lgkmcnt(0)
	s_barrier
	ds_read_b128 a[12:15], v82 offset:4096
	ds_read_b128 a[8:11], v82
	ds_read_b128 a[4:7], v83 offset:36864
	ds_read_b128 a[0:3], v83 offset:32768
	v_mfma_f32_32x32x16_bf16 v[16:31], a[16:19], a[28:31], v[16:31]
	v_mfma_f32_32x32x16_bf16 v[0:15], a[20:23], a[28:31], v[0:15]
	s_nop 0
	s_nop 0
	s_nop 0
	s_nop 0
	ds_read_b128 a[16:19], v85 offset:32768
	ds_read_b128 a[20:23], v85 offset:36864
	ds_read_b128 a[24:27], v84
	ds_read_b128 a[28:31], v84 offset:4096
	s_waitcnt lgkmcnt(4)
	v_mfma_f32_32x32x16_bf16 v[48:63], a[0:3], a[8:11], v[48:63]
	v_mfma_f32_32x32x16_bf16 v[32:47], a[4:7], a[8:11], v[32:47]
	v_mfma_f32_32x32x16_bf16 v[16:31], a[0:3], a[12:15], v[16:31]
	v_mfma_f32_32x32x16_bf16 v[0:15], a[4:7], a[12:15], v[0:15]
	s_nop 0
	s_nop 0
	s_nop 0
	s_nop 0
	ds_read_b128 a[0:3], v87 offset:32768
	ds_read_b128 a[4:7], v87 offset:36864
	ds_read_b128 a[8:11], v86
	ds_read_b128 a[12:15], v86 offset:4096
	s_waitcnt lgkmcnt(5)
	v_mfma_f32_32x32x16_bf16 v[48:63], a[16:19], a[24:27], v[48:63]
	v_mfma_f32_32x32x16_bf16 v[32:47], a[20:23], a[24:27], v[32:47]
	s_waitcnt lgkmcnt(4)
	v_mfma_f32_32x32x16_bf16 v[16:31], a[16:19], a[28:31], v[16:31]
	v_mfma_f32_32x32x16_bf16 v[0:15], a[20:23], a[28:31], v[0:15]
	s_nop 0
	s_nop 0
	s_nop 0
	s_waitcnt lgkmcnt(1)
	v_mfma_f32_32x32x16_bf16 v[48:63], a[0:3], a[8:11], v[48:63]
	v_mfma_f32_32x32x16_bf16 v[32:47], a[4:7], a[8:11], v[32:47]
	s_nop 0
	s_waitcnt lgkmcnt(0)
	v_mfma_f32_32x32x16_bf16 v[0:15], a[4:7], a[12:15], v[0:15]
	v_mfma_f32_32x32x16_bf16 v[16:31], a[0:3], a[12:15], v[16:31]
	ds_read_b128 v[66:69], v89 offset:32768
	ds_read_b128 v[70:73], v88
	ds_read_b128 v[74:77], v89 offset:36864
	ds_read_b128 v[82:85], v88 offset:4096
	s_waitcnt lgkmcnt(0)
	s_barrier
	s_waitcnt lgkmcnt(0)
	v_mfma_f32_32x32x16_bf16 v[48:63], v[66:69], v[70:73], v[48:63]
	v_mfma_f32_32x32x16_bf16 v[32:47], v[74:77], v[70:73], v[32:47]
	s_nop 10
	ds_write_b128 v64, v[48:51]
	ds_write_b128 v64, v[52:55] offset:32
	ds_write_b128 v64, v[56:59] offset:64
	ds_write_b128 v64, v[60:63] offset:96
	ds_write_b128 v64, v[32:35] offset:128
	v_mfma_f32_32x32x16_bf16 v[0:15], v[74:77], v[82:85], v[0:15]
	v_mfma_f32_32x32x16_bf16 v[16:31], v[66:69], v[82:85], v[16:31]
	s_setprio 0
	ds_write_b128 v64, v[36:39] offset:160
	ds_write_b128 v64, v[40:43] offset:192
	ds_write_b128 v64, v[44:47] offset:224
	s_nop 8
	ds_write_b128 v64, v[16:19] offset:16896
	ds_write_b128 v64, v[20:23] offset:16928
	ds_write_b128 v64, v[24:27] offset:16960
	ds_write_b128 v64, v[28:31] offset:16992
	ds_write_b128 v64, v[0:3] offset:17024
	ds_write_b128 v64, v[4:7] offset:17056
	ds_write_b128 v64, v[8:11] offset:17088
	ds_write_b128 v64, v[12:15] offset:17120
	s_waitcnt lgkmcnt(0)
	s_barrier
	v_lshl_or_b32 v0, v79, 2, s31
	v_ashrrev_i32_e32 v1, 31, v0
	v_lshl_add_u32 v4, v79, 4, 0
	v_lshl_add_u64 v[6:7], v[0:1], 2, s[92:93]
	v_lshl_add_u64 v[8:9], v[0:1], 1, s[20:21]
	s_branch .LBB0_161
